# speedup vs baseline: 1.0222x; 1.0057x over previous
; #define WAIT_V(n) asm volatile("s_waitcnt vmcnt(" #n ")" ::: "memory")
; #define WAIT_L(n) asm volatile("s_waitcnt lgkmcnt(" #n ")" ::: "memory")
; #define BAR __builtin_amdgcn_s_barrier()
; #define SCHED __builtin_amdgcn_sched_barrier(0)
; #define STAGE_A(b, h, kt)                                        \
;   do {                                                           \
;     const char* _g = Ab + (h) * halfK + (long)(kt) * 128;        \
;     GLDS2(_g, (unsigned)(((b) * 2 + (h)) * 16384));              \
;   } while (0)
; #define STAGE_B(b, h, kt)                                        \
;   do {                                                           \
;     const char* _g = Bb + (h) * halfK + (long)(kt) * 128;        \
;     GLDS2(_g, (unsigned)(65536 + ((b) * 2 + (h)) * 16384));      \
;   } while (0)
; #define LDA(dst, b, h)                                                                                   \
;   _Pragma("unroll") for (int m = 0; m < 4; ++m) _Pragma("unroll") for (int k = 0; k < 2; ++k) dst[m][k] = \
;       *reinterpret_cast<const bf16x8*>(aRd + ((b) * 2 + (h)) * 16384 + m * 2048 + k * 1024)
; #define LDB(dst, b, h)                                                                                   \
;   _Pragma("unroll") for (int n = 0; n < 2; ++n) _Pragma("unroll") for (int k = 0; k < 2; ++k) dst[n][k] = \
;       *reinterpret_cast<const bf16x8*>(bRd + ((b) * 2 + (h)) * 16384 + n * 2048 + k * 1024)
; template <int EPI> ...
;     ...
;     LDB(B0, 0, 0);
;     SCHED;
;     LDA(At, 0, 0);
;     STAGE_A(1, 1, t + 1);
;     WAIT_L(8);
;     BAR;
;     WAIT_L(0);
;     MMA(0, 0, At, B0);
;     BAR;
;     SCHED;
;     LDB(B1, 0, 1);
;     STAGE_B(0, 0, t + 2);
;     BAR;
;     WAIT_L(0);
;     MMA(0, 1, At, B1);
;     BAR;
;     LDA(At, 0, 1);
;     STAGE_A(0, 0, t + 2);
;     BAR;
;     WAIT_L(0);
;     MMA(1, 0, At, B0);
;     BAR;
;     SCHED;
;     STAGE_B(0, 1, t + 2);
;     WAIT_V(6);
;     BAR;
.LBB0_114:
	ds_read_b128 v[138:141], v137
	ds_read_b128 v[142:145], v137 offset:1024
	ds_read_b128 v[146:149], v137 offset:2048
	ds_read_b128 v[150:153], v137 offset:3072
	ds_read_b128 v[154:157], v136
	ds_read_b128 v[158:161], v136 offset:1024
	ds_read_b128 v[162:165], v136 offset:2048
	ds_read_b128 v[166:169], v136 offset:3072
	ds_read_b128 v[170:173], v136 offset:4096
	ds_read_b128 v[174:177], v136 offset:5120
	ds_read_b128 v[178:181], v136 offset:6144
	ds_read_b128 v[182:185], v136 offset:7168
	s_add_u32 s22, s11, s12
	s_addc_u32 s23, s37, s13
	s_add_u32 s74, s22, 0x80
	s_addc_u32 s75, s23, 0
	s_mov_b32 m0, s77
	s_nop 0
	global_load_lds_dwordx4 v132, s[74:75]
	s_nop 0
	s_mov_b32 m0, s64
	s_nop 0
	global_load_lds_dwordx4 v130, s[74:75]
	s_waitcnt lgkmcnt(8)
	s_barrier
	s_waitcnt lgkmcnt(0)
	v_mfma_f32_16x16x32_bf16 v[126:129], v[138:141], v[154:157], v[126:129]
	v_mfma_f32_16x16x32_bf16 v[126:129], v[142:145], v[158:161], v[126:129]
	v_mfma_f32_16x16x32_bf16 v[122:125], v[150:153], v[158:161], v[122:125]
	v_mfma_f32_16x16x32_bf16 v[122:125], v[146:149], v[154:157], v[122:125]
	v_mfma_f32_16x16x32_bf16 v[114:117], v[146:149], v[162:165], v[114:117]
	v_mfma_f32_16x16x32_bf16 v[114:117], v[150:153], v[166:169], v[114:117]
	v_mfma_f32_16x16x32_bf16 v[118:121], v[142:145], v[166:169], v[118:121]
	v_mfma_f32_16x16x32_bf16 v[118:121], v[138:141], v[162:165], v[118:121]
	v_mfma_f32_16x16x32_bf16 v[110:113], v[138:141], v[170:173], v[110:113]
	v_mfma_f32_16x16x32_bf16 v[110:113], v[142:145], v[174:177], v[110:113]
	v_mfma_f32_16x16x32_bf16 v[106:109], v[150:153], v[174:177], v[106:109]
	v_mfma_f32_16x16x32_bf16 v[106:109], v[146:149], v[170:173], v[106:109]
	v_mfma_f32_16x16x32_bf16 v[98:101], v[146:149], v[178:181], v[98:101]
	v_mfma_f32_16x16x32_bf16 v[98:101], v[150:153], v[182:185], v[98:101]
	v_mfma_f32_16x16x32_bf16 v[102:105], v[142:145], v[182:185], v[102:105]
	v_mfma_f32_16x16x32_bf16 v[102:105], v[138:141], v[178:181], v[102:105]
	s_barrier
	ds_read_b128 v[186:189], v137 offset:16384
	ds_read_b128 v[196:199], v137 offset:17408
	ds_read_b128 v[212:215], v137 offset:18432
	ds_read_b128 v[220:223], v137 offset:19456
	s_add_u32 s49, s98, s12
	s_addc_u32 s54, s99, s13
	s_add_u32 s74, s49, 0x100
	s_addc_u32 s75, s54, 0
	s_mov_b32 m0, s20
	s_nop 0
	global_load_lds_dwordx4 v132, s[74:75]
	s_nop 0
	s_mov_b32 m0, s21
	s_nop 0
	global_load_lds_dwordx4 v130, s[74:75]
	s_barrier
	s_waitcnt lgkmcnt(0)
	v_mfma_f32_16x16x32_bf16 v[94:97], v[186:189], v[154:157], v[94:97]
	v_mfma_f32_16x16x32_bf16 v[94:97], v[196:199], v[158:161], v[94:97]
	v_mfma_f32_16x16x32_bf16 v[90:93], v[220:223], v[158:161], v[90:93]
	v_mfma_f32_16x16x32_bf16 v[90:93], v[212:215], v[154:157], v[90:93]
	v_mfma_f32_16x16x32_bf16 v[82:85], v[212:215], v[162:165], v[82:85]
	v_mfma_f32_16x16x32_bf16 v[82:85], v[220:223], v[166:169], v[82:85]
	v_mfma_f32_16x16x32_bf16 v[86:89], v[196:199], v[166:169], v[86:89]
	v_mfma_f32_16x16x32_bf16 v[86:89], v[186:189], v[162:165], v[86:89]
	v_mfma_f32_16x16x32_bf16 v[78:81], v[186:189], v[170:173], v[78:81]
	v_mfma_f32_16x16x32_bf16 v[78:81], v[196:199], v[174:177], v[78:81]
	v_mfma_f32_16x16x32_bf16 v[74:77], v[220:223], v[174:177], v[74:77]
	v_mfma_f32_16x16x32_bf16 v[74:77], v[212:215], v[170:173], v[74:77]
	v_mfma_f32_16x16x32_bf16 v[66:69], v[212:215], v[178:181], v[66:69]
	v_mfma_f32_16x16x32_bf16 v[66:69], v[220:223], v[182:185], v[66:69]
	v_mfma_f32_16x16x32_bf16 v[70:73], v[196:199], v[182:185], v[70:73]
	v_mfma_f32_16x16x32_bf16 v[70:73], v[186:189], v[178:181], v[70:73]
	s_barrier
	ds_read_b128 v[154:157], v136 offset:16384
	ds_read_b128 v[158:161], v136 offset:17408
	ds_read_b128 v[162:165], v136 offset:18432
	ds_read_b128 v[166:169], v136 offset:19456
	ds_read_b128 v[170:173], v136 offset:20480
	ds_read_b128 v[174:177], v136 offset:21504
	ds_read_b128 v[178:181], v136 offset:22528
	ds_read_b128 v[182:185], v136 offset:23552
	s_add_u32 s60, s96, s12
	s_addc_u32 s68, s97, s13
	s_add_u32 s74, s60, 0x100
	s_addc_u32 s75, s68, 0
	s_mov_b32 m0, s2
	s_nop 0
	global_load_lds_dwordx4 v132, s[74:75]
	s_nop 0
	s_mov_b32 m0, s38
	s_nop 0
	global_load_lds_dwordx4 v130, s[74:75]
	s_barrier
	s_waitcnt lgkmcnt(0)
	v_mfma_f32_16x16x32_bf16 v[62:65], v[138:141], v[154:157], v[62:65]
	v_mfma_f32_16x16x32_bf16 v[62:65], v[142:145], v[158:161], v[62:65]
	v_mfma_f32_16x16x32_bf16 v[58:61], v[150:153], v[158:161], v[58:61]
	v_mfma_f32_16x16x32_bf16 v[58:61], v[146:149], v[154:157], v[58:61]
	v_mfma_f32_16x16x32_bf16 v[50:53], v[146:149], v[162:165], v[50:53]
	v_mfma_f32_16x16x32_bf16 v[50:53], v[150:153], v[166:169], v[50:53]
	v_mfma_f32_16x16x32_bf16 v[54:57], v[142:145], v[166:169], v[54:57]
	v_mfma_f32_16x16x32_bf16 v[54:57], v[138:141], v[162:165], v[54:57]
	v_mfma_f32_16x16x32_bf16 v[46:49], v[138:141], v[170:173], v[46:49]
	v_mfma_f32_16x16x32_bf16 v[46:49], v[142:145], v[174:177], v[46:49]
	v_mfma_f32_16x16x32_bf16 v[42:45], v[150:153], v[174:177], v[42:45]
	v_mfma_f32_16x16x32_bf16 v[42:45], v[146:149], v[170:173], v[42:45]
	v_mfma_f32_16x16x32_bf16 v[34:37], v[146:149], v[178:181], v[34:37]
	v_mfma_f32_16x16x32_bf16 v[34:37], v[150:153], v[182:185], v[34:37]
	v_mfma_f32_16x16x32_bf16 v[38:41], v[142:145], v[182:185], v[38:41]
	v_mfma_f32_16x16x32_bf16 v[38:41], v[138:141], v[178:181], v[38:41]
	s_barrier
	s_add_u32 s69, s7, s12
	s_addc_u32 s76, s8, s13
	s_add_u32 s74, s69, 0x100
	s_addc_u32 s75, s76, 0
	s_mov_b32 m0, s39
	s_nop 0
	global_load_lds_dwordx4 v132, s[74:75]
	s_nop 0
	s_mov_b32 m0, s28
	s_nop 0
	global_load_lds_dwordx4 v130, s[74:75]
	s_waitcnt vmcnt(6)
	s_barrier
; #define WAIT_L(n) asm volatile("s_waitcnt lgkmcnt(" #n ")" ::: "memory")
; #define BAR __builtin_amdgcn_s_barrier()
; #define SCHED __builtin_amdgcn_sched_barrier(0)
; #define STAGE_A(b, h, kt)                                        \
;   do {                                                           \
;     const char* _g = Ab + (h) * halfK + (long)(kt) * 128;        \
;     GLDS2(_g, (unsigned)(((b) * 2 + (h)) * 16384));              \
;   } while (0)
; #define STAGE_B(b, h, kt)                                        \
;   do {                                                           \
;     const char* _g = Bb + (h) * halfK + (long)(kt) * 128;        \
;     GLDS2(_g, (unsigned)(65536 + ((b) * 2 + (h)) * 16384));      \
;   } while (0)
; #define LDA(dst, b, h)                                                                                   \
;   _Pragma("unroll") for (int m = 0; m < 4; ++m) _Pragma("unroll") for (int k = 0; k < 2; ++k) dst[m][k] = \
;       *reinterpret_cast<const bf16x8*>(aRd + ((b) * 2 + (h)) * 16384 + m * 2048 + k * 1024)
; #define LDB(dst, b, h)                                                                                   \
;   _Pragma("unroll") for (int n = 0; n < 2; ++n) _Pragma("unroll") for (int k = 0; k < 2; ++k) dst[n][k] = \
;       *reinterpret_cast<const bf16x8*>(bRd + ((b) * 2 + (h)) * 16384 + n * 2048 + k * 1024)
; template <int EPI> ...
;     ...
;     MMA(1, 1, At, B1);
;     BAR;
;     LDB(B0, 1, 0);
;     SCHED;
;     LDA(At, 1, 0);
;     STAGE_A(0, 1, t + 2);
;     WAIT_L(8);
;     BAR;
;     WAIT_L(0);
;     MMA(0, 0, At, B0);
;     BAR;
;     SCHED;
;     LDB(B1, 1, 1);
;     STAGE_B(1, 0, t + 3);
;     BAR;
;     WAIT_L(0);
;     MMA(0, 1, At, B1);
;     BAR;
;     LDA(At, 1, 1);
;     STAGE_A(1, 0, t + 3);
;     BAR;
	v_mfma_f32_16x16x32_bf16 v[30:33], v[186:189], v[154:157], v[30:33]
	v_mfma_f32_16x16x32_bf16 v[30:33], v[196:199], v[158:161], v[30:33]
	v_mfma_f32_16x16x32_bf16 v[26:29], v[220:223], v[158:161], v[26:29]
	v_mfma_f32_16x16x32_bf16 v[26:29], v[212:215], v[154:157], v[26:29]
	v_mfma_f32_16x16x32_bf16 v[18:21], v[212:215], v[162:165], v[18:21]
	v_mfma_f32_16x16x32_bf16 v[18:21], v[220:223], v[166:169], v[18:21]
	v_mfma_f32_16x16x32_bf16 v[22:25], v[196:199], v[166:169], v[22:25]
	v_mfma_f32_16x16x32_bf16 v[22:25], v[186:189], v[162:165], v[22:25]
	v_mfma_f32_16x16x32_bf16 v[14:17], v[186:189], v[170:173], v[14:17]
	v_mfma_f32_16x16x32_bf16 v[14:17], v[196:199], v[174:177], v[14:17]
	v_mfma_f32_16x16x32_bf16 v[10:13], v[220:223], v[174:177], v[10:13]
	v_mfma_f32_16x16x32_bf16 v[10:13], v[212:215], v[170:173], v[10:13]
	v_mfma_f32_16x16x32_bf16 v[2:5], v[212:215], v[178:181], v[2:5]
	v_mfma_f32_16x16x32_bf16 v[2:5], v[220:223], v[182:185], v[2:5]
	v_mfma_f32_16x16x32_bf16 v[6:9], v[196:199], v[182:185], v[6:9]
	v_mfma_f32_16x16x32_bf16 v[6:9], v[186:189], v[178:181], v[6:9]
	s_barrier
	ds_read_b128 v[138:141], v137 offset:32768
	ds_read_b128 v[142:145], v137 offset:33792
	ds_read_b128 v[146:149], v137 offset:34816
	ds_read_b128 v[150:153], v137 offset:35840
	ds_read_b128 v[154:157], v136 offset:32768
	ds_read_b128 v[158:161], v136 offset:33792
	ds_read_b128 v[162:165], v136 offset:34816
	ds_read_b128 v[166:169], v136 offset:35840
	ds_read_b128 v[170:173], v136 offset:36864
	ds_read_b128 v[174:177], v136 offset:37888
	ds_read_b128 v[178:181], v136 offset:38912
	ds_read_b128 v[182:185], v136 offset:39936
	s_add_u32 s74, s22, 0x100
	s_addc_u32 s75, s23, 0
	s_mov_b32 m0, s29
	s_nop 0
	global_load_lds_dwordx4 v132, s[74:75]
	s_nop 0
	s_mov_b32 m0, s62
	s_nop 0
	global_load_lds_dwordx4 v130, s[74:75]
	s_waitcnt lgkmcnt(8)
	s_barrier
	s_waitcnt lgkmcnt(0)
	v_mfma_f32_16x16x32_bf16 v[126:129], v[138:141], v[154:157], v[126:129]
	v_mfma_f32_16x16x32_bf16 v[126:129], v[142:145], v[158:161], v[126:129]
	v_mfma_f32_16x16x32_bf16 v[122:125], v[150:153], v[158:161], v[122:125]
	v_mfma_f32_16x16x32_bf16 v[122:125], v[146:149], v[154:157], v[122:125]
	v_mfma_f32_16x16x32_bf16 v[114:117], v[146:149], v[162:165], v[114:117]
	v_mfma_f32_16x16x32_bf16 v[114:117], v[150:153], v[166:169], v[114:117]
	v_mfma_f32_16x16x32_bf16 v[118:121], v[142:145], v[166:169], v[118:121]
	v_mfma_f32_16x16x32_bf16 v[118:121], v[138:141], v[162:165], v[118:121]
	v_mfma_f32_16x16x32_bf16 v[110:113], v[138:141], v[170:173], v[110:113]
	v_mfma_f32_16x16x32_bf16 v[110:113], v[142:145], v[174:177], v[110:113]
	v_mfma_f32_16x16x32_bf16 v[106:109], v[150:153], v[174:177], v[106:109]
	v_mfma_f32_16x16x32_bf16 v[106:109], v[146:149], v[170:173], v[106:109]
	v_mfma_f32_16x16x32_bf16 v[98:101], v[146:149], v[178:181], v[98:101]
	v_mfma_f32_16x16x32_bf16 v[98:101], v[150:153], v[182:185], v[98:101]
	v_mfma_f32_16x16x32_bf16 v[102:105], v[142:145], v[182:185], v[102:105]
	v_mfma_f32_16x16x32_bf16 v[102:105], v[138:141], v[178:181], v[102:105]
	s_barrier
	ds_read_b128 v[186:189], v137 offset:49152
	ds_read_b128 v[196:199], v137 offset:50176
	ds_read_b128 v[212:215], v137 offset:51200
	ds_read_b128 v[220:223], v137 offset:52224
	s_add_u32 s74, s49, 0x180
	s_addc_u32 s75, s54, 0
	s_mov_b32 m0, s50
	s_nop 0
	global_load_lds_dwordx4 v132, s[74:75]
	s_nop 0
	s_mov_b32 m0, s51
	s_nop 0
	global_load_lds_dwordx4 v130, s[74:75]
	s_barrier
	s_waitcnt lgkmcnt(0)
	v_mfma_f32_16x16x32_bf16 v[94:97], v[186:189], v[154:157], v[94:97]
	v_mfma_f32_16x16x32_bf16 v[94:97], v[196:199], v[158:161], v[94:97]
	v_mfma_f32_16x16x32_bf16 v[90:93], v[220:223], v[158:161], v[90:93]
	v_mfma_f32_16x16x32_bf16 v[90:93], v[212:215], v[154:157], v[90:93]
	v_mfma_f32_16x16x32_bf16 v[82:85], v[212:215], v[162:165], v[82:85]
	v_mfma_f32_16x16x32_bf16 v[82:85], v[220:223], v[166:169], v[82:85]
	v_mfma_f32_16x16x32_bf16 v[86:89], v[196:199], v[166:169], v[86:89]
	v_mfma_f32_16x16x32_bf16 v[86:89], v[186:189], v[162:165], v[86:89]
	v_mfma_f32_16x16x32_bf16 v[78:81], v[186:189], v[170:173], v[78:81]
	v_mfma_f32_16x16x32_bf16 v[78:81], v[196:199], v[174:177], v[78:81]
	v_mfma_f32_16x16x32_bf16 v[74:77], v[220:223], v[174:177], v[74:77]
	v_mfma_f32_16x16x32_bf16 v[74:77], v[212:215], v[170:173], v[74:77]
	v_mfma_f32_16x16x32_bf16 v[66:69], v[212:215], v[178:181], v[66:69]
	v_mfma_f32_16x16x32_bf16 v[66:69], v[220:223], v[182:185], v[66:69]
	v_mfma_f32_16x16x32_bf16 v[70:73], v[196:199], v[182:185], v[70:73]
	v_mfma_f32_16x16x32_bf16 v[70:73], v[186:189], v[178:181], v[70:73]
	s_barrier
	ds_read_b128 v[154:157], v136 offset:49152
	ds_read_b128 v[158:161], v136 offset:50176
	ds_read_b128 v[162:165], v136 offset:51200
	ds_read_b128 v[166:169], v136 offset:52224
	ds_read_b128 v[170:173], v136 offset:53248
	ds_read_b128 v[174:177], v136 offset:54272
	ds_read_b128 v[178:181], v136 offset:55296
	ds_read_b128 v[182:185], v136 offset:56320
	s_add_u32 s74, s60, 0x180
	s_addc_u32 s75, s68, 0
	s_mov_b32 m0, s63
	s_nop 0
	global_load_lds_dwordx4 v132, s[74:75]
	s_nop 0
	s_mov_b32 m0, s6
	s_nop 0
	global_load_lds_dwordx4 v130, s[74:75]
	s_barrier
; #define WAIT_V(n) asm volatile("s_waitcnt vmcnt(" #n ")" ::: "memory")
; #define WAIT_L(n) asm volatile("s_waitcnt lgkmcnt(" #n ")" ::: "memory")
; #define BAR __builtin_amdgcn_s_barrier()
; #define SCHED __builtin_amdgcn_sched_barrier(0)
; #define STAGE_A(b, h, kt)                                        \
;   do {                                                           \
;     const char* _g = Ab + (h) * halfK + (long)(kt) * 128;        \
;     GLDS2(_g, (unsigned)(((b) * 2 + (h)) * 16384));              \
;   } while (0)
; #define STAGE_B(b, h, kt)                                        \
;   do {                                                           \
;     const char* _g = Bb + (h) * halfK + (long)(kt) * 128;        \
;     GLDS2(_g, (unsigned)(65536 + ((b) * 2 + (h)) * 16384));      \
;   } while (0)
; #define LDA(dst, b, h)                                                                                   \
;   _Pragma("unroll") for (int m = 0; m < 4; ++m) _Pragma("unroll") for (int k = 0; k < 2; ++k) dst[m][k] = \
;       *reinterpret_cast<const bf16x8*>(aRd + ((b) * 2 + (h)) * 16384 + m * 2048 + k * 1024)
; #define LDB(dst, b, h)                                                                                   \
;   _Pragma("unroll") for (int n = 0; n < 2; ++n) _Pragma("unroll") for (int k = 0; k < 2; ++k) dst[n][k] = \
;       *reinterpret_cast<const bf16x8*>(bRd + ((b) * 2 + (h)) * 16384 + n * 2048 + k * 1024)
; template <int EPI> ...
;     ...
;     WAIT_L(0);
;     MMA(1, 0, At, B0);
;     BAR;
;     SCHED;
;     STAGE_B(1, 1, t + 3);
;     WAIT_V(6);
;     BAR;
;     MMA(1, 1, At, B1);
;     BAR;
;   }
;   {
;     LDB(B0, 0, 0);
;     LDA(At, 0, 0);
;     STAGE_A(1, 1, nt - 1);
;     BAR;
;     WAIT_L(0);
;     MMA(0, 0, At, B0);
;     BAR;
;     LDB(B1, 0, 1);
;     BAR;
;     WAIT_L(0);
;     MMA(0, 1, At, B1);
;     BAR;
	s_waitcnt lgkmcnt(0)
	v_mfma_f32_16x16x32_bf16 v[62:65], v[138:141], v[154:157], v[62:65]
	v_mfma_f32_16x16x32_bf16 v[62:65], v[142:145], v[158:161], v[62:65]
	v_mfma_f32_16x16x32_bf16 v[58:61], v[150:153], v[158:161], v[58:61]
	v_mfma_f32_16x16x32_bf16 v[58:61], v[146:149], v[154:157], v[58:61]
	v_mfma_f32_16x16x32_bf16 v[50:53], v[146:149], v[162:165], v[50:53]
	v_mfma_f32_16x16x32_bf16 v[50:53], v[150:153], v[166:169], v[50:53]
	v_mfma_f32_16x16x32_bf16 v[54:57], v[142:145], v[166:169], v[54:57]
	v_mfma_f32_16x16x32_bf16 v[54:57], v[138:141], v[162:165], v[54:57]
	v_mfma_f32_16x16x32_bf16 v[46:49], v[138:141], v[170:173], v[46:49]
	v_mfma_f32_16x16x32_bf16 v[46:49], v[142:145], v[174:177], v[46:49]
	v_mfma_f32_16x16x32_bf16 v[42:45], v[150:153], v[174:177], v[42:45]
	v_mfma_f32_16x16x32_bf16 v[42:45], v[146:149], v[170:173], v[42:45]
	v_mfma_f32_16x16x32_bf16 v[34:37], v[146:149], v[178:181], v[34:37]
	v_mfma_f32_16x16x32_bf16 v[34:37], v[150:153], v[182:185], v[34:37]
	v_mfma_f32_16x16x32_bf16 v[38:41], v[142:145], v[182:185], v[38:41]
	v_mfma_f32_16x16x32_bf16 v[38:41], v[138:141], v[178:181], v[38:41]
	s_barrier
	s_add_u32 s74, s69, 0x180
	s_addc_u32 s75, s76, 0
	s_mov_b32 m0, s9
	s_nop 0
	global_load_lds_dwordx4 v132, s[74:75]
	s_nop 0
	s_mov_b32 m0, s10
	s_nop 0
	global_load_lds_dwordx4 v130, s[74:75]
	s_waitcnt vmcnt(6)
	s_barrier
	v_mfma_f32_16x16x32_bf16 v[30:33], v[186:189], v[154:157], v[30:33]
	v_mfma_f32_16x16x32_bf16 v[30:33], v[196:199], v[158:161], v[30:33]
	v_mfma_f32_16x16x32_bf16 v[26:29], v[220:223], v[158:161], v[26:29]
	v_mfma_f32_16x16x32_bf16 v[26:29], v[212:215], v[154:157], v[26:29]
	v_mfma_f32_16x16x32_bf16 v[18:21], v[212:215], v[162:165], v[18:21]
	v_mfma_f32_16x16x32_bf16 v[18:21], v[220:223], v[166:169], v[18:21]
	v_mfma_f32_16x16x32_bf16 v[22:25], v[196:199], v[166:169], v[22:25]
	v_mfma_f32_16x16x32_bf16 v[22:25], v[186:189], v[162:165], v[22:25]
	v_mfma_f32_16x16x32_bf16 v[14:17], v[186:189], v[170:173], v[14:17]
	v_mfma_f32_16x16x32_bf16 v[14:17], v[196:199], v[174:177], v[14:17]
	v_mfma_f32_16x16x32_bf16 v[10:13], v[220:223], v[174:177], v[10:13]
	v_mfma_f32_16x16x32_bf16 v[10:13], v[212:215], v[170:173], v[10:13]
	v_mfma_f32_16x16x32_bf16 v[2:5], v[212:215], v[178:181], v[2:5]
	v_mfma_f32_16x16x32_bf16 v[2:5], v[220:223], v[182:185], v[2:5]
	v_mfma_f32_16x16x32_bf16 v[6:9], v[196:199], v[182:185], v[6:9]
	v_mfma_f32_16x16x32_bf16 v[6:9], v[186:189], v[178:181], v[6:9]
	s_add_i32 s91, s91, 2
	s_add_u32 s12, s12, 0x100
	s_addc_u32 s13, s13, 0
	s_cmp_lt_u32 s91, 28
	s_barrier
	s_cbranch_scc1 .LBB0_114
	ds_read_b128 v[138:141], v137
	ds_read_b128 v[142:145], v137 offset:1024
	ds_read_b128 v[146:149], v137 offset:2048
	ds_read_b128 v[150:153], v137 offset:3072
	ds_read_b128 v[154:157], v136
	ds_read_b128 v[158:161], v136 offset:1024
	ds_read_b128 v[162:165], v136 offset:2048
	ds_read_b128 v[166:169], v136 offset:3072
	ds_read_b128 v[170:173], v136 offset:4096
	ds_read_b128 v[174:177], v136 offset:5120
	ds_read_b128 v[178:181], v136 offset:6144
	ds_read_b128 v[182:185], v136 offset:7168
	s_add_u32 s6, s96, 0x80f80
	s_addc_u32 s7, s97, 0
	s_mov_b32 m0, s77
	s_nop 0
	global_load_lds_dwordx4 v132, s[6:7]
	s_nop 0
	s_mov_b32 m0, s64
	s_nop 0
	global_load_lds_dwordx4 v130, s[6:7]
	s_barrier
	s_waitcnt lgkmcnt(0)
	v_mfma_f32_16x16x32_bf16 v[126:129], v[138:141], v[154:157], v[126:129]
	v_mfma_f32_16x16x32_bf16 v[126:129], v[142:145], v[158:161], v[126:129]
	v_mfma_f32_16x16x32_bf16 v[122:125], v[150:153], v[158:161], v[122:125]
	v_mfma_f32_16x16x32_bf16 v[122:125], v[146:149], v[154:157], v[122:125]
	v_mfma_f32_16x16x32_bf16 v[114:117], v[146:149], v[162:165], v[114:117]
	v_mfma_f32_16x16x32_bf16 v[114:117], v[150:153], v[166:169], v[114:117]
	v_mfma_f32_16x16x32_bf16 v[118:121], v[142:145], v[166:169], v[118:121]
	v_mfma_f32_16x16x32_bf16 v[118:121], v[138:141], v[162:165], v[118:121]
	v_mfma_f32_16x16x32_bf16 v[110:113], v[138:141], v[170:173], v[110:113]
	v_mfma_f32_16x16x32_bf16 v[110:113], v[142:145], v[174:177], v[110:113]
	v_mfma_f32_16x16x32_bf16 v[106:109], v[150:153], v[174:177], v[106:109]
	v_mfma_f32_16x16x32_bf16 v[106:109], v[146:149], v[170:173], v[106:109]
	v_mfma_f32_16x16x32_bf16 v[98:101], v[146:149], v[178:181], v[98:101]
	v_mfma_f32_16x16x32_bf16 v[98:101], v[150:153], v[182:185], v[98:101]
	v_mfma_f32_16x16x32_bf16 v[102:105], v[142:145], v[182:185], v[102:105]
	v_mfma_f32_16x16x32_bf16 v[102:105], v[138:141], v[178:181], v[102:105]
	s_barrier
	ds_read_b128 v[186:189], v137 offset:16384
	ds_read_b128 v[196:199], v137 offset:17408
	ds_read_b128 v[212:215], v137 offset:18432
	ds_read_b128 v[220:223], v137 offset:19456
	s_barrier
	s_waitcnt lgkmcnt(0)
	v_mfma_f32_16x16x32_bf16 v[94:97], v[186:189], v[154:157], v[94:97]
	v_mfma_f32_16x16x32_bf16 v[94:97], v[196:199], v[158:161], v[94:97]
	v_mfma_f32_16x16x32_bf16 v[90:93], v[220:223], v[158:161], v[90:93]
	v_mfma_f32_16x16x32_bf16 v[90:93], v[212:215], v[154:157], v[90:93]
	v_mfma_f32_16x16x32_bf16 v[82:85], v[212:215], v[162:165], v[82:85]
	v_mfma_f32_16x16x32_bf16 v[82:85], v[220:223], v[166:169], v[82:85]
	v_mfma_f32_16x16x32_bf16 v[86:89], v[196:199], v[166:169], v[86:89]
	v_mfma_f32_16x16x32_bf16 v[86:89], v[186:189], v[162:165], v[86:89]
	v_mfma_f32_16x16x32_bf16 v[78:81], v[186:189], v[170:173], v[78:81]
	v_mfma_f32_16x16x32_bf16 v[78:81], v[196:199], v[174:177], v[78:81]
	v_mfma_f32_16x16x32_bf16 v[74:77], v[220:223], v[174:177], v[74:77]
	v_mfma_f32_16x16x32_bf16 v[74:77], v[212:215], v[170:173], v[74:77]
	v_mfma_f32_16x16x32_bf16 v[66:69], v[212:215], v[178:181], v[66:69]
	v_mfma_f32_16x16x32_bf16 v[66:69], v[220:223], v[182:185], v[66:69]
	v_mfma_f32_16x16x32_bf16 v[70:73], v[196:199], v[182:185], v[70:73]
	v_mfma_f32_16x16x32_bf16 v[70:73], v[186:189], v[178:181], v[70:73]
	s_barrier
; #define WAIT_V(n) asm volatile("s_waitcnt vmcnt(" #n ")" ::: "memory")
; #define WAIT_L(n) asm volatile("s_waitcnt lgkmcnt(" #n ")" ::: "memory")
; #define BAR __builtin_amdgcn_s_barrier()
; #define LDA(dst, b, h)                                                                                   \
;   _Pragma("unroll") for (int m = 0; m < 4; ++m) _Pragma("unroll") for (int k = 0; k < 2; ++k) dst[m][k] = \
;       *reinterpret_cast<const bf16x8*>(aRd + ((b) * 2 + (h)) * 16384 + m * 2048 + k * 1024)
; #define LDB(dst, b, h)                                                                                   \
;   _Pragma("unroll") for (int n = 0; n < 2; ++n) _Pragma("unroll") for (int k = 0; k < 2; ++k) dst[n][k] = \
;       *reinterpret_cast<const bf16x8*>(bRd + ((b) * 2 + (h)) * 16384 + n * 2048 + k * 1024)
; template <int EPI> ...
;     ...
;     LDA(At, 0, 1);
;     WAIT_V(4);
;     BAR;
;     WAIT_L(0);
;     MMA(1, 0, At, B0);
;     MMA(1, 1, At, B1);
;     BAR;
;   }
;   {
;     LDB(B0, 1, 0);
;     LDA(At, 1, 0);
;     WAIT_V(2);
;     BAR;
;     WAIT_L(0);
;     MMA(0, 0, At, B0);
	ds_read_b128 v[154:157], v136 offset:16384
	ds_read_b128 v[158:161], v136 offset:17408
	ds_read_b128 v[162:165], v136 offset:18432
	ds_read_b128 v[166:169], v136 offset:19456
	ds_read_b128 v[170:173], v136 offset:20480
	ds_read_b128 v[174:177], v136 offset:21504
	ds_read_b128 v[178:181], v136 offset:22528
	ds_read_b128 v[182:185], v136 offset:23552
	s_waitcnt vmcnt(4)
	s_barrier
	s_waitcnt lgkmcnt(0)
	v_mfma_f32_16x16x32_bf16 v[62:65], v[138:141], v[154:157], v[62:65]
	v_mfma_f32_16x16x32_bf16 v[62:65], v[142:145], v[158:161], v[62:65]
	v_mfma_f32_16x16x32_bf16 v[58:61], v[150:153], v[158:161], v[58:61]
	v_mfma_f32_16x16x32_bf16 v[58:61], v[146:149], v[154:157], v[58:61]
	v_mfma_f32_16x16x32_bf16 v[50:53], v[146:149], v[162:165], v[50:53]
	v_mfma_f32_16x16x32_bf16 v[50:53], v[150:153], v[166:169], v[50:53]
	v_mfma_f32_16x16x32_bf16 v[54:57], v[142:145], v[166:169], v[54:57]
	v_mfma_f32_16x16x32_bf16 v[54:57], v[138:141], v[162:165], v[54:57]
	v_mfma_f32_16x16x32_bf16 v[46:49], v[138:141], v[170:173], v[46:49]
	v_mfma_f32_16x16x32_bf16 v[46:49], v[142:145], v[174:177], v[46:49]
	v_mfma_f32_16x16x32_bf16 v[42:45], v[150:153], v[174:177], v[42:45]
	v_mfma_f32_16x16x32_bf16 v[42:45], v[146:149], v[170:173], v[42:45]
	v_mfma_f32_16x16x32_bf16 v[34:37], v[146:149], v[178:181], v[34:37]
	v_mfma_f32_16x16x32_bf16 v[34:37], v[150:153], v[182:185], v[34:37]
	v_mfma_f32_16x16x32_bf16 v[38:41], v[142:145], v[182:185], v[38:41]
	v_mfma_f32_16x16x32_bf16 v[38:41], v[138:141], v[178:181], v[38:41]
	v_mfma_f32_16x16x32_bf16 v[30:33], v[186:189], v[154:157], v[30:33]
	v_mfma_f32_16x16x32_bf16 v[30:33], v[196:199], v[158:161], v[30:33]
	v_mfma_f32_16x16x32_bf16 v[26:29], v[220:223], v[158:161], v[26:29]
	v_mfma_f32_16x16x32_bf16 v[26:29], v[212:215], v[154:157], v[26:29]
	v_mfma_f32_16x16x32_bf16 v[18:21], v[212:215], v[162:165], v[18:21]
	v_mfma_f32_16x16x32_bf16 v[18:21], v[220:223], v[166:169], v[18:21]
	v_mfma_f32_16x16x32_bf16 v[22:25], v[196:199], v[166:169], v[22:25]
	v_mfma_f32_16x16x32_bf16 v[22:25], v[186:189], v[162:165], v[22:25]
	v_mfma_f32_16x16x32_bf16 v[14:17], v[186:189], v[170:173], v[14:17]
	v_mfma_f32_16x16x32_bf16 v[14:17], v[196:199], v[174:177], v[14:17]
	v_mfma_f32_16x16x32_bf16 v[10:13], v[220:223], v[174:177], v[10:13]
	v_mfma_f32_16x16x32_bf16 v[10:13], v[212:215], v[170:173], v[10:13]
	v_mfma_f32_16x16x32_bf16 v[2:5], v[212:215], v[178:181], v[2:5]
	v_mfma_f32_16x16x32_bf16 v[2:5], v[220:223], v[182:185], v[2:5]
	v_mfma_f32_16x16x32_bf16 v[6:9], v[196:199], v[182:185], v[6:9]
	v_mfma_f32_16x16x32_bf16 v[6:9], v[186:189], v[178:181], v[6:9]
	s_barrier
	ds_read_b128 v[138:141], v137 offset:32768
	ds_read_b128 v[142:145], v137 offset:33792
	ds_read_b128 v[146:149], v137 offset:34816
	ds_read_b128 v[150:153], v137 offset:35840
	ds_read_b128 v[154:157], v136 offset:32768
	ds_read_b128 v[158:161], v136 offset:33792
	ds_read_b128 v[162:165], v136 offset:34816
	ds_read_b128 v[166:169], v136 offset:35840
	ds_read_b128 v[170:173], v136 offset:36864
	ds_read_b128 v[174:177], v136 offset:37888
	ds_read_b128 v[178:181], v136 offset:38912
	ds_read_b128 v[182:185], v136 offset:39936
	s_waitcnt vmcnt(2)
	s_barrier
	s_waitcnt lgkmcnt(0)
	v_mfma_f32_16x16x32_bf16 v[126:129], v[138:141], v[154:157], v[126:129]
	v_mfma_f32_16x16x32_bf16 v[126:129], v[142:145], v[158:161], v[126:129]
	v_mfma_f32_16x16x32_bf16 v[122:125], v[150:153], v[158:161], v[122:125]
	v_mfma_f32_16x16x32_bf16 v[122:125], v[146:149], v[154:157], v[122:125]
	v_mfma_f32_16x16x32_bf16 v[114:117], v[146:149], v[162:165], v[114:117]
	v_mfma_f32_16x16x32_bf16 v[114:117], v[150:153], v[166:169], v[114:117]
	v_mfma_f32_16x16x32_bf16 v[118:121], v[142:145], v[166:169], v[118:121]
	v_mfma_f32_16x16x32_bf16 v[118:121], v[138:141], v[162:165], v[118:121]
	v_mfma_f32_16x16x32_bf16 v[110:113], v[138:141], v[170:173], v[110:113]
	v_mfma_f32_16x16x32_bf16 v[110:113], v[142:145], v[174:177], v[110:113]
	v_mfma_f32_16x16x32_bf16 v[106:109], v[150:153], v[174:177], v[106:109]
	v_mfma_f32_16x16x32_bf16 v[106:109], v[146:149], v[170:173], v[106:109]
	v_mfma_f32_16x16x32_bf16 v[98:101], v[146:149], v[178:181], v[98:101]
	v_mfma_f32_16x16x32_bf16 v[98:101], v[150:153], v[182:185], v[98:101]
	v_mfma_f32_16x16x32_bf16 v[102:105], v[142:145], v[182:185], v[102:105]
	v_mfma_f32_16x16x32_bf16 v[102:105], v[138:141], v[178:181], v[102:105]
	s_barrier
; #define WAIT_V(n) asm volatile("s_waitcnt vmcnt(" #n ")" ::: "memory")
; #define WAIT_L(n) asm volatile("s_waitcnt lgkmcnt(" #n ")" ::: "memory")
; #define BAR __builtin_amdgcn_s_barrier()
; #define LDA(dst, b, h)                                                                                   \
;   _Pragma("unroll") for (int m = 0; m < 4; ++m) _Pragma("unroll") for (int k = 0; k < 2; ++k) dst[m][k] = \
;       *reinterpret_cast<const bf16x8*>(aRd + ((b) * 2 + (h)) * 16384 + m * 2048 + k * 1024)
; #define LDB(dst, b, h)                                                                                   \
;   _Pragma("unroll") for (int n = 0; n < 2; ++n) _Pragma("unroll") for (int k = 0; k < 2; ++k) dst[n][k] = \
;       *reinterpret_cast<const bf16x8*>(bRd + ((b) * 2 + (h)) * 16384 + n * 2048 + k * 1024)
; template <int EPI> ...
;     ...
;     LDB(B1, 1, 1);
;     WAIT_V(0);
;     BAR;
;     WAIT_L(0);
;     MMA(0, 1, At, B1);
;     BAR;
;     LDA(At, 1, 1);
;     BAR;
;     WAIT_L(0);
;     MMA(1, 0, At, B0);
;     MMA(1, 1, At, B1);
;     BAR;
;   }
;   if (wr == 0) BAR;
	ds_read_b128 v[186:189], v137 offset:49152
	ds_read_b128 v[196:199], v137 offset:50176
	ds_read_b128 v[212:215], v137 offset:51200
	ds_read_b128 v[220:223], v137 offset:52224
	s_waitcnt vmcnt(0)
	s_barrier
	s_waitcnt lgkmcnt(0)
	v_mfma_f32_16x16x32_bf16 v[94:97], v[186:189], v[154:157], v[94:97]
	v_mfma_f32_16x16x32_bf16 v[94:97], v[196:199], v[158:161], v[94:97]
	v_mfma_f32_16x16x32_bf16 v[90:93], v[220:223], v[158:161], v[90:93]
	v_mfma_f32_16x16x32_bf16 v[90:93], v[212:215], v[154:157], v[90:93]
	v_mfma_f32_16x16x32_bf16 v[82:85], v[212:215], v[162:165], v[82:85]
	v_mfma_f32_16x16x32_bf16 v[82:85], v[220:223], v[166:169], v[82:85]
	v_mfma_f32_16x16x32_bf16 v[86:89], v[196:199], v[166:169], v[86:89]
	v_mfma_f32_16x16x32_bf16 v[86:89], v[186:189], v[162:165], v[86:89]
	v_mfma_f32_16x16x32_bf16 v[78:81], v[186:189], v[170:173], v[78:81]
	v_mfma_f32_16x16x32_bf16 v[78:81], v[196:199], v[174:177], v[78:81]
	v_mfma_f32_16x16x32_bf16 v[74:77], v[220:223], v[174:177], v[74:77]
	v_mfma_f32_16x16x32_bf16 v[74:77], v[212:215], v[170:173], v[74:77]
	v_mfma_f32_16x16x32_bf16 v[66:69], v[212:215], v[178:181], v[66:69]
	v_mfma_f32_16x16x32_bf16 v[66:69], v[220:223], v[182:185], v[66:69]
	v_mfma_f32_16x16x32_bf16 v[70:73], v[196:199], v[182:185], v[70:73]
	v_mfma_f32_16x16x32_bf16 v[70:73], v[186:189], v[178:181], v[70:73]
	s_barrier
	ds_read_b128 v[154:157], v136 offset:49152
	ds_read_b128 v[158:161], v136 offset:50176
	ds_read_b128 v[162:165], v136 offset:51200
	ds_read_b128 v[166:169], v136 offset:52224
	ds_read_b128 v[170:173], v136 offset:53248
	ds_read_b128 v[174:177], v136 offset:54272
	ds_read_b128 v[178:181], v136 offset:55296
	ds_read_b128 v[182:185], v136 offset:56320
	s_barrier
	s_waitcnt lgkmcnt(0)
	v_mfma_f32_16x16x32_bf16 v[62:65], v[138:141], v[154:157], v[62:65]
	v_mfma_f32_16x16x32_bf16 v[62:65], v[142:145], v[158:161], v[62:65]
	v_mfma_f32_16x16x32_bf16 v[58:61], v[150:153], v[158:161], v[58:61]
	v_mfma_f32_16x16x32_bf16 v[58:61], v[146:149], v[154:157], v[58:61]
	v_mfma_f32_16x16x32_bf16 v[50:53], v[146:149], v[162:165], v[50:53]
	v_mfma_f32_16x16x32_bf16 v[50:53], v[150:153], v[166:169], v[50:53]
	v_mfma_f32_16x16x32_bf16 v[54:57], v[142:145], v[166:169], v[54:57]
	v_mfma_f32_16x16x32_bf16 v[54:57], v[138:141], v[162:165], v[54:57]
	v_mfma_f32_16x16x32_bf16 v[46:49], v[138:141], v[170:173], v[46:49]
	v_mfma_f32_16x16x32_bf16 v[46:49], v[142:145], v[174:177], v[46:49]
	v_mfma_f32_16x16x32_bf16 v[42:45], v[150:153], v[174:177], v[42:45]
	v_mfma_f32_16x16x32_bf16 v[42:45], v[146:149], v[170:173], v[42:45]
	v_mfma_f32_16x16x32_bf16 v[34:37], v[146:149], v[178:181], v[34:37]
	v_mfma_f32_16x16x32_bf16 v[34:37], v[150:153], v[182:185], v[34:37]
	v_mfma_f32_16x16x32_bf16 v[38:41], v[142:145], v[182:185], v[38:41]
	v_mfma_f32_16x16x32_bf16 v[38:41], v[138:141], v[178:181], v[38:41]
	v_mfma_f32_16x16x32_bf16 v[30:33], v[186:189], v[154:157], v[30:33]
	v_mfma_f32_16x16x32_bf16 v[30:33], v[196:199], v[158:161], v[30:33]
	v_mfma_f32_16x16x32_bf16 v[26:29], v[220:223], v[158:161], v[26:29]
	v_mfma_f32_16x16x32_bf16 v[26:29], v[212:215], v[154:157], v[26:29]
	v_mfma_f32_16x16x32_bf16 v[18:21], v[212:215], v[162:165], v[18:21]
	v_mfma_f32_16x16x32_bf16 v[18:21], v[220:223], v[166:169], v[18:21]
	v_mfma_f32_16x16x32_bf16 v[22:25], v[196:199], v[166:169], v[22:25]
	v_mfma_f32_16x16x32_bf16 v[22:25], v[186:189], v[162:165], v[22:25]
	v_mfma_f32_16x16x32_bf16 v[14:17], v[186:189], v[170:173], v[14:17]
	v_mfma_f32_16x16x32_bf16 v[14:17], v[196:199], v[174:177], v[14:17]
	v_mfma_f32_16x16x32_bf16 v[10:13], v[220:223], v[174:177], v[10:13]
	v_mfma_f32_16x16x32_bf16 v[10:13], v[212:215], v[170:173], v[10:13]
	v_mfma_f32_16x16x32_bf16 v[2:5], v[212:215], v[178:181], v[2:5]
	v_mfma_f32_16x16x32_bf16 v[2:5], v[220:223], v[182:185], v[2:5]
	v_mfma_f32_16x16x32_bf16 v[6:9], v[196:199], v[182:185], v[6:9]
	v_mfma_f32_16x16x32_bf16 v[6:9], v[186:189], v[178:181], v[6:9]
	s_movk_i32 s6, 0x100
	v_cmp_gt_u32_e32 vcc, s6, v134
	s_barrier
	s_and_saveexec_b64 s[12:13], vcc
	s_cbranch_execz .LBB0_117
	s_barrier

; #define WAIT_V(n) asm volatile("s_waitcnt vmcnt(" #n ")" ::: "memory")
; #define WAIT_L(n) asm volatile("s_waitcnt lgkmcnt(" #n ")" ::: "memory")
; #define BAR __builtin_amdgcn_s_barrier()
; #define SCHED __builtin_amdgcn_sched_barrier(0)
; #define STAGE_A(b, h, kt)                                        \
;   do {                                                           \
;     const char* _g = Ab + (h) * halfK + (long)(kt) * 128;        \
;     GLDS2(_g, (unsigned)(((b) * 2 + (h)) * 16384));              \
;   } while (0)
; #define STAGE_B(b, h, kt)                                        \
;   do {                                                           \
;     const char* _g = Bb + (h) * halfK + (long)(kt) * 128;        \
;     GLDS2(_g, (unsigned)(65536 + ((b) * 2 + (h)) * 16384));      \
;   } while (0)
; #define LDA(dst, b, h)                                                                                   \
;   _Pragma("unroll") for (int m = 0; m < 4; ++m) _Pragma("unroll") for (int k = 0; k < 2; ++k) dst[m][k] = \
;       *reinterpret_cast<const bf16x8*>(aRd + ((b) * 2 + (h)) * 16384 + m * 2048 + k * 1024)
; #define LDB(dst, b, h)                                                                                   \
;   _Pragma("unroll") for (int n = 0; n < 2; ++n) _Pragma("unroll") for (int k = 0; k < 2; ++k) dst[n][k] = \
;       *reinterpret_cast<const bf16x8*>(bRd + ((b) * 2 + (h)) * 16384 + n * 2048 + k * 1024)
; template <int EPI> ...
;     ...
;     LDB(B0, 0, 0);
;     SCHED;
;     LDA(At, 0, 0);
;     STAGE_A(1, 1, t + 1);
;     WAIT_L(8);
;     BAR;
;     WAIT_L(0);
;     MMA(0, 0, At, B0);
;     BAR;
;     SCHED;
;     LDB(B1, 0, 1);
;     STAGE_B(0, 0, t + 2);
;     BAR;
;     WAIT_L(0);
;     MMA(0, 1, At, B1);
;     BAR;
;     LDA(At, 0, 1);
;     STAGE_A(0, 0, t + 2);
;     BAR;
;     WAIT_L(0);
;     MMA(1, 0, At, B0);
;     BAR;
;     SCHED;
;     STAGE_B(0, 1, t + 2);
;     WAIT_V(6);
;     BAR;
.LBB0_203:
	ds_read_b128 v[138:141], v137
	ds_read_b128 v[142:145], v137 offset:1024
	ds_read_b128 v[146:149], v137 offset:2048
	ds_read_b128 v[150:153], v137 offset:3072
	ds_read_b128 v[154:157], v136
	ds_read_b128 v[158:161], v136 offset:1024
	ds_read_b128 v[162:165], v136 offset:2048
	ds_read_b128 v[166:169], v136 offset:3072
	ds_read_b128 v[170:173], v136 offset:4096
	ds_read_b128 v[174:177], v136 offset:5120
	ds_read_b128 v[178:181], v136 offset:6144
	ds_read_b128 v[182:185], v136 offset:7168
	s_add_u32 s76, s6, s12
	s_addc_u32 s60, s7, s13
	s_add_u32 s74, s76, 0x80
	s_addc_u32 s75, s60, 0
	s_mov_b32 m0, vcc_lo
	s_nop 0
	global_load_lds_dwordx4 v132, s[74:75]
	s_nop 0
	s_mov_b32 m0, s92
	s_nop 0
	global_load_lds_dwordx4 v131, s[74:75]
	s_waitcnt lgkmcnt(8)
	s_barrier
	s_waitcnt lgkmcnt(0)
	v_mfma_f32_16x16x32_bf16 v[126:129], v[138:141], v[154:157], v[126:129]
	v_mfma_f32_16x16x32_bf16 v[126:129], v[142:145], v[158:161], v[126:129]
	v_mfma_f32_16x16x32_bf16 v[122:125], v[150:153], v[158:161], v[122:125]
	v_mfma_f32_16x16x32_bf16 v[122:125], v[146:149], v[154:157], v[122:125]
	v_mfma_f32_16x16x32_bf16 v[114:117], v[146:149], v[162:165], v[114:117]
	v_mfma_f32_16x16x32_bf16 v[114:117], v[150:153], v[166:169], v[114:117]
	v_mfma_f32_16x16x32_bf16 v[118:121], v[142:145], v[166:169], v[118:121]
	v_mfma_f32_16x16x32_bf16 v[118:121], v[138:141], v[162:165], v[118:121]
	v_mfma_f32_16x16x32_bf16 v[110:113], v[138:141], v[170:173], v[110:113]
	v_mfma_f32_16x16x32_bf16 v[110:113], v[142:145], v[174:177], v[110:113]
	v_mfma_f32_16x16x32_bf16 v[106:109], v[150:153], v[174:177], v[106:109]
	v_mfma_f32_16x16x32_bf16 v[106:109], v[146:149], v[170:173], v[106:109]
	v_mfma_f32_16x16x32_bf16 v[98:101], v[146:149], v[178:181], v[98:101]
	v_mfma_f32_16x16x32_bf16 v[98:101], v[150:153], v[182:185], v[98:101]
	v_mfma_f32_16x16x32_bf16 v[102:105], v[142:145], v[182:185], v[102:105]
	v_mfma_f32_16x16x32_bf16 v[102:105], v[138:141], v[178:181], v[102:105]
	s_barrier
	s_add_i32 s34, s34, 2
	ds_read_b128 v[186:189], v137 offset:16384
	ds_read_b128 v[220:223], v137 offset:17408
	ds_read_b128 v[224:227], v137 offset:18432
	ds_read_b128 v[228:231], v137 offset:19456
	s_add_u32 s49, s88, s12
	s_addc_u32 s22, s89, s13
	s_add_u32 s74, s49, 0x100
	s_addc_u32 s75, s22, 0
	s_mov_b32 m0, s20
	s_nop 0
	global_load_lds_dwordx4 v132, s[74:75]
	s_nop 0
	s_mov_b32 m0, s21
	s_nop 0
	global_load_lds_dwordx4 v131, s[74:75]
	s_barrier
	s_waitcnt lgkmcnt(0)
	v_mfma_f32_16x16x32_bf16 v[94:97], v[186:189], v[154:157], v[94:97]
	v_mfma_f32_16x16x32_bf16 v[94:97], v[220:223], v[158:161], v[94:97]
	v_mfma_f32_16x16x32_bf16 v[90:93], v[228:231], v[158:161], v[90:93]
	v_mfma_f32_16x16x32_bf16 v[90:93], v[224:227], v[154:157], v[90:93]
	v_mfma_f32_16x16x32_bf16 v[82:85], v[224:227], v[162:165], v[82:85]
	v_mfma_f32_16x16x32_bf16 v[82:85], v[228:231], v[166:169], v[82:85]
	v_mfma_f32_16x16x32_bf16 v[86:89], v[220:223], v[166:169], v[86:89]
	v_mfma_f32_16x16x32_bf16 v[86:89], v[186:189], v[162:165], v[86:89]
	v_mfma_f32_16x16x32_bf16 v[78:81], v[186:189], v[170:173], v[78:81]
	v_mfma_f32_16x16x32_bf16 v[78:81], v[220:223], v[174:177], v[78:81]
	v_mfma_f32_16x16x32_bf16 v[74:77], v[228:231], v[174:177], v[74:77]
	v_mfma_f32_16x16x32_bf16 v[74:77], v[224:227], v[170:173], v[74:77]
	v_mfma_f32_16x16x32_bf16 v[66:69], v[224:227], v[178:181], v[66:69]
	v_mfma_f32_16x16x32_bf16 v[66:69], v[228:231], v[182:185], v[66:69]
	v_mfma_f32_16x16x32_bf16 v[70:73], v[220:223], v[182:185], v[70:73]
	v_mfma_f32_16x16x32_bf16 v[70:73], v[186:189], v[178:181], v[70:73]
	s_barrier
	ds_read_b128 v[154:157], v136 offset:16384
	ds_read_b128 v[158:161], v136 offset:17408
	ds_read_b128 v[162:165], v136 offset:18432
	ds_read_b128 v[166:169], v136 offset:19456
	ds_read_b128 v[170:173], v136 offset:20480
	ds_read_b128 v[174:177], v136 offset:21504
	ds_read_b128 v[178:181], v136 offset:22528
	ds_read_b128 v[182:185], v136 offset:23552
	s_add_u32 s23, s90, s12
	s_addc_u32 s68, s91, s13
	s_add_u32 s74, s23, 0x100
	s_addc_u32 s75, s68, 0
	s_mov_b32 m0, s63
	s_nop 0
	global_load_lds_dwordx4 v132, s[74:75]
	s_nop 0
	s_mov_b32 m0, s78
	s_nop 0
	global_load_lds_dwordx4 v131, s[74:75]
	s_barrier
	s_waitcnt lgkmcnt(0)
	v_mfma_f32_16x16x32_bf16 v[62:65], v[138:141], v[154:157], v[62:65]
	v_mfma_f32_16x16x32_bf16 v[62:65], v[142:145], v[158:161], v[62:65]
	v_mfma_f32_16x16x32_bf16 v[58:61], v[150:153], v[158:161], v[58:61]
	v_mfma_f32_16x16x32_bf16 v[58:61], v[146:149], v[154:157], v[58:61]
	v_mfma_f32_16x16x32_bf16 v[50:53], v[146:149], v[162:165], v[50:53]
	v_mfma_f32_16x16x32_bf16 v[50:53], v[150:153], v[166:169], v[50:53]
	v_mfma_f32_16x16x32_bf16 v[54:57], v[142:145], v[166:169], v[54:57]
	v_mfma_f32_16x16x32_bf16 v[54:57], v[138:141], v[162:165], v[54:57]
	v_mfma_f32_16x16x32_bf16 v[46:49], v[138:141], v[170:173], v[46:49]
	v_mfma_f32_16x16x32_bf16 v[46:49], v[142:145], v[174:177], v[46:49]
	v_mfma_f32_16x16x32_bf16 v[42:45], v[150:153], v[174:177], v[42:45]
	v_mfma_f32_16x16x32_bf16 v[42:45], v[146:149], v[170:173], v[42:45]
	v_mfma_f32_16x16x32_bf16 v[34:37], v[146:149], v[178:181], v[34:37]
	v_mfma_f32_16x16x32_bf16 v[34:37], v[150:153], v[182:185], v[34:37]
	v_mfma_f32_16x16x32_bf16 v[38:41], v[142:145], v[182:185], v[38:41]
	v_mfma_f32_16x16x32_bf16 v[38:41], v[138:141], v[178:181], v[38:41]
	s_barrier
	s_add_u32 s69, s8, s12
	s_addc_u32 s54, s9, s13
	s_add_u32 s74, s69, 0x100
	s_addc_u32 s75, s54, 0
	s_mov_b32 m0, s79
	s_nop 0
	global_load_lds_dwordx4 v132, s[74:75]
	s_nop 0
	s_mov_b32 m0, s38
	s_nop 0
	global_load_lds_dwordx4 v131, s[74:75]
	s_waitcnt vmcnt(6)
	s_barrier
; #define WAIT_L(n) asm volatile("s_waitcnt lgkmcnt(" #n ")" ::: "memory")
; #define BAR __builtin_amdgcn_s_barrier()
; #define SCHED __builtin_amdgcn_sched_barrier(0)
; #define STAGE_A(b, h, kt)                                        \
;   do {                                                           \
;     const char* _g = Ab + (h) * halfK + (long)(kt) * 128;        \
;     GLDS2(_g, (unsigned)(((b) * 2 + (h)) * 16384));              \
;   } while (0)
; #define STAGE_B(b, h, kt)                                        \
;   do {                                                           \
;     const char* _g = Bb + (h) * halfK + (long)(kt) * 128;        \
;     GLDS2(_g, (unsigned)(65536 + ((b) * 2 + (h)) * 16384));      \
;   } while (0)
; #define LDA(dst, b, h)                                                                                   \
;   _Pragma("unroll") for (int m = 0; m < 4; ++m) _Pragma("unroll") for (int k = 0; k < 2; ++k) dst[m][k] = \
;       *reinterpret_cast<const bf16x8*>(aRd + ((b) * 2 + (h)) * 16384 + m * 2048 + k * 1024)
; #define LDB(dst, b, h)                                                                                   \
;   _Pragma("unroll") for (int n = 0; n < 2; ++n) _Pragma("unroll") for (int k = 0; k < 2; ++k) dst[n][k] = \
;       *reinterpret_cast<const bf16x8*>(bRd + ((b) * 2 + (h)) * 16384 + n * 2048 + k * 1024)
; template <int EPI> ...
;     ...
;     MMA(1, 1, At, B1);
;     BAR;
;     LDB(B0, 1, 0);
;     SCHED;
;     LDA(At, 1, 0);
;     STAGE_A(0, 1, t + 2);
;     WAIT_L(8);
;     BAR;
;     WAIT_L(0);
;     MMA(0, 0, At, B0);
;     BAR;
;     SCHED;
;     LDB(B1, 1, 1);
;     STAGE_B(1, 0, t + 3);
;     BAR;
;     WAIT_L(0);
;     MMA(0, 1, At, B1);
;     BAR;
;     LDA(At, 1, 1);
;     STAGE_A(1, 0, t + 3);
;     BAR;
	v_mfma_f32_16x16x32_bf16 v[30:33], v[186:189], v[154:157], v[30:33]
	v_mfma_f32_16x16x32_bf16 v[30:33], v[220:223], v[158:161], v[30:33]
	v_mfma_f32_16x16x32_bf16 v[26:29], v[228:231], v[158:161], v[26:29]
	v_mfma_f32_16x16x32_bf16 v[26:29], v[224:227], v[154:157], v[26:29]
	v_mfma_f32_16x16x32_bf16 v[18:21], v[224:227], v[162:165], v[18:21]
	v_mfma_f32_16x16x32_bf16 v[18:21], v[228:231], v[166:169], v[18:21]
	v_mfma_f32_16x16x32_bf16 v[22:25], v[220:223], v[166:169], v[22:25]
	v_mfma_f32_16x16x32_bf16 v[22:25], v[186:189], v[162:165], v[22:25]
	v_mfma_f32_16x16x32_bf16 v[14:17], v[186:189], v[170:173], v[14:17]
	v_mfma_f32_16x16x32_bf16 v[14:17], v[220:223], v[174:177], v[14:17]
	v_mfma_f32_16x16x32_bf16 v[10:13], v[228:231], v[174:177], v[10:13]
	v_mfma_f32_16x16x32_bf16 v[10:13], v[224:227], v[170:173], v[10:13]
	v_mfma_f32_16x16x32_bf16 v[2:5], v[224:227], v[178:181], v[2:5]
	v_mfma_f32_16x16x32_bf16 v[2:5], v[228:231], v[182:185], v[2:5]
	v_mfma_f32_16x16x32_bf16 v[6:9], v[220:223], v[182:185], v[6:9]
	v_mfma_f32_16x16x32_bf16 v[6:9], v[186:189], v[178:181], v[6:9]
	s_barrier
	ds_read_b128 v[138:141], v137 offset:32768
	ds_read_b128 v[142:145], v137 offset:33792
	ds_read_b128 v[146:149], v137 offset:34816
	ds_read_b128 v[150:153], v137 offset:35840
	ds_read_b128 v[154:157], v136 offset:32768
	ds_read_b128 v[158:161], v136 offset:33792
	ds_read_b128 v[162:165], v136 offset:34816
	ds_read_b128 v[166:169], v136 offset:35840
	ds_read_b128 v[170:173], v136 offset:36864
	ds_read_b128 v[174:177], v136 offset:37888
	ds_read_b128 v[178:181], v136 offset:38912
	ds_read_b128 v[182:185], v136 offset:39936
	s_add_u32 s74, s76, 0x100
	s_addc_u32 s75, s60, 0
	s_mov_b32 m0, s39
	s_nop 0
	global_load_lds_dwordx4 v132, s[74:75]
	s_nop 0
	s_mov_b32 m0, s28
	s_nop 0
	global_load_lds_dwordx4 v131, s[74:75]
	s_waitcnt lgkmcnt(8)
	s_barrier
	s_waitcnt lgkmcnt(0)
	v_mfma_f32_16x16x32_bf16 v[126:129], v[138:141], v[154:157], v[126:129]
	v_mfma_f32_16x16x32_bf16 v[126:129], v[142:145], v[158:161], v[126:129]
	v_mfma_f32_16x16x32_bf16 v[122:125], v[150:153], v[158:161], v[122:125]
	v_mfma_f32_16x16x32_bf16 v[122:125], v[146:149], v[154:157], v[122:125]
	v_mfma_f32_16x16x32_bf16 v[114:117], v[146:149], v[162:165], v[114:117]
	v_mfma_f32_16x16x32_bf16 v[114:117], v[150:153], v[166:169], v[114:117]
	v_mfma_f32_16x16x32_bf16 v[118:121], v[142:145], v[166:169], v[118:121]
	v_mfma_f32_16x16x32_bf16 v[118:121], v[138:141], v[162:165], v[118:121]
	v_mfma_f32_16x16x32_bf16 v[110:113], v[138:141], v[170:173], v[110:113]
	v_mfma_f32_16x16x32_bf16 v[110:113], v[142:145], v[174:177], v[110:113]
	v_mfma_f32_16x16x32_bf16 v[106:109], v[150:153], v[174:177], v[106:109]
	v_mfma_f32_16x16x32_bf16 v[106:109], v[146:149], v[170:173], v[106:109]
	v_mfma_f32_16x16x32_bf16 v[98:101], v[146:149], v[178:181], v[98:101]
	v_mfma_f32_16x16x32_bf16 v[98:101], v[150:153], v[182:185], v[98:101]
	v_mfma_f32_16x16x32_bf16 v[102:105], v[142:145], v[182:185], v[102:105]
	v_mfma_f32_16x16x32_bf16 v[102:105], v[138:141], v[178:181], v[102:105]
	s_barrier
	ds_read_b128 v[186:189], v137 offset:49152
	ds_read_b128 v[220:223], v137 offset:50176
	ds_read_b128 v[224:227], v137 offset:51200
	ds_read_b128 v[228:231], v137 offset:52224
	s_add_u32 s74, s49, 0x180
	s_addc_u32 s75, s22, 0
	s_mov_b32 m0, s50
	s_nop 0
	global_load_lds_dwordx4 v132, s[74:75]
	s_nop 0
	s_mov_b32 m0, s51
	s_nop 0
	global_load_lds_dwordx4 v131, s[74:75]
	s_barrier
	s_waitcnt lgkmcnt(0)
	v_mfma_f32_16x16x32_bf16 v[94:97], v[186:189], v[154:157], v[94:97]
	v_mfma_f32_16x16x32_bf16 v[94:97], v[220:223], v[158:161], v[94:97]
	v_mfma_f32_16x16x32_bf16 v[90:93], v[228:231], v[158:161], v[90:93]
	v_mfma_f32_16x16x32_bf16 v[90:93], v[224:227], v[154:157], v[90:93]
	v_mfma_f32_16x16x32_bf16 v[82:85], v[224:227], v[162:165], v[82:85]
	v_mfma_f32_16x16x32_bf16 v[82:85], v[228:231], v[166:169], v[82:85]
	v_mfma_f32_16x16x32_bf16 v[86:89], v[220:223], v[166:169], v[86:89]
	v_mfma_f32_16x16x32_bf16 v[86:89], v[186:189], v[162:165], v[86:89]
	v_mfma_f32_16x16x32_bf16 v[78:81], v[186:189], v[170:173], v[78:81]
	v_mfma_f32_16x16x32_bf16 v[78:81], v[220:223], v[174:177], v[78:81]
	v_mfma_f32_16x16x32_bf16 v[74:77], v[228:231], v[174:177], v[74:77]
	v_mfma_f32_16x16x32_bf16 v[74:77], v[224:227], v[170:173], v[74:77]
	v_mfma_f32_16x16x32_bf16 v[66:69], v[224:227], v[178:181], v[66:69]
	v_mfma_f32_16x16x32_bf16 v[66:69], v[228:231], v[182:185], v[66:69]
	v_mfma_f32_16x16x32_bf16 v[70:73], v[220:223], v[182:185], v[70:73]
	v_mfma_f32_16x16x32_bf16 v[70:73], v[186:189], v[178:181], v[70:73]
	s_barrier
	ds_read_b128 v[154:157], v136 offset:49152
	ds_read_b128 v[158:161], v136 offset:50176
	ds_read_b128 v[162:165], v136 offset:51200
	ds_read_b128 v[166:169], v136 offset:52224
	ds_read_b128 v[170:173], v136 offset:53248
	ds_read_b128 v[174:177], v136 offset:54272
	ds_read_b128 v[178:181], v136 offset:55296
	ds_read_b128 v[182:185], v136 offset:56320
	s_add_u32 s74, s23, 0x180
	s_addc_u32 s75, s68, 0
	s_mov_b32 m0, s93
	s_nop 0
	global_load_lds_dwordx4 v132, s[74:75]
	s_nop 0
	s_mov_b32 m0, vcc_hi
	s_nop 0
	global_load_lds_dwordx4 v131, s[74:75]
	s_barrier
; #define WAIT_V(n) asm volatile("s_waitcnt vmcnt(" #n ")" ::: "memory")
; #define WAIT_L(n) asm volatile("s_waitcnt lgkmcnt(" #n ")" ::: "memory")
; #define BAR __builtin_amdgcn_s_barrier()
; #define SCHED __builtin_amdgcn_sched_barrier(0)
; #define STAGE_A(b, h, kt)                                        \
;   do {                                                           \
;     const char* _g = Ab + (h) * halfK + (long)(kt) * 128;        \
;     GLDS2(_g, (unsigned)(((b) * 2 + (h)) * 16384));              \
;   } while (0)
; #define STAGE_B(b, h, kt)                                        \
;   do {                                                           \
;     const char* _g = Bb + (h) * halfK + (long)(kt) * 128;        \
;     GLDS2(_g, (unsigned)(65536 + ((b) * 2 + (h)) * 16384));      \
;   } while (0)
; #define LDA(dst, b, h)                                                                                   \
;   _Pragma("unroll") for (int m = 0; m < 4; ++m) _Pragma("unroll") for (int k = 0; k < 2; ++k) dst[m][k] = \
;       *reinterpret_cast<const bf16x8*>(aRd + ((b) * 2 + (h)) * 16384 + m * 2048 + k * 1024)
; #define LDB(dst, b, h)                                                                                   \
;   _Pragma("unroll") for (int n = 0; n < 2; ++n) _Pragma("unroll") for (int k = 0; k < 2; ++k) dst[n][k] = \
;       *reinterpret_cast<const bf16x8*>(bRd + ((b) * 2 + (h)) * 16384 + n * 2048 + k * 1024)
; template <int EPI> ...
;     ...
;     WAIT_L(0);
;     MMA(1, 0, At, B0);
;     BAR;
;     SCHED;
;     STAGE_B(1, 1, t + 3);
;     WAIT_V(6);
;     BAR;
;     MMA(1, 1, At, B1);
;     BAR;
;   }
;   {
;     LDB(B0, 0, 0);
;     LDA(At, 0, 0);
;     STAGE_A(1, 1, nt - 1);
;     BAR;
;     WAIT_L(0);
;     MMA(0, 0, At, B0);
;     BAR;
;     LDB(B1, 0, 1);
;     BAR;
;     WAIT_L(0);
;     MMA(0, 1, At, B1);
;     BAR;
	s_waitcnt lgkmcnt(0)
	v_mfma_f32_16x16x32_bf16 v[62:65], v[138:141], v[154:157], v[62:65]
	v_mfma_f32_16x16x32_bf16 v[62:65], v[142:145], v[158:161], v[62:65]
	v_mfma_f32_16x16x32_bf16 v[58:61], v[150:153], v[158:161], v[58:61]
	v_mfma_f32_16x16x32_bf16 v[58:61], v[146:149], v[154:157], v[58:61]
	v_mfma_f32_16x16x32_bf16 v[50:53], v[146:149], v[162:165], v[50:53]
	v_mfma_f32_16x16x32_bf16 v[50:53], v[150:153], v[166:169], v[50:53]
	v_mfma_f32_16x16x32_bf16 v[54:57], v[142:145], v[166:169], v[54:57]
	v_mfma_f32_16x16x32_bf16 v[54:57], v[138:141], v[162:165], v[54:57]
	v_mfma_f32_16x16x32_bf16 v[46:49], v[138:141], v[170:173], v[46:49]
	v_mfma_f32_16x16x32_bf16 v[46:49], v[142:145], v[174:177], v[46:49]
	v_mfma_f32_16x16x32_bf16 v[42:45], v[150:153], v[174:177], v[42:45]
	v_mfma_f32_16x16x32_bf16 v[42:45], v[146:149], v[170:173], v[42:45]
	v_mfma_f32_16x16x32_bf16 v[34:37], v[146:149], v[178:181], v[34:37]
	v_mfma_f32_16x16x32_bf16 v[34:37], v[150:153], v[182:185], v[34:37]
	v_mfma_f32_16x16x32_bf16 v[38:41], v[142:145], v[182:185], v[38:41]
	v_mfma_f32_16x16x32_bf16 v[38:41], v[138:141], v[178:181], v[38:41]
	s_barrier
	s_add_u32 s74, s69, 0x180
	s_addc_u32 s75, s54, 0
	s_mov_b32 m0, s10
	s_nop 0
	global_load_lds_dwordx4 v132, s[74:75]
	s_nop 0
	s_mov_b32 m0, s11
	s_nop 0
	global_load_lds_dwordx4 v131, s[74:75]
	s_waitcnt vmcnt(6)
	s_barrier
	v_mfma_f32_16x16x32_bf16 v[30:33], v[186:189], v[154:157], v[30:33]
	v_mfma_f32_16x16x32_bf16 v[30:33], v[220:223], v[158:161], v[30:33]
	v_mfma_f32_16x16x32_bf16 v[26:29], v[228:231], v[158:161], v[26:29]
	v_mfma_f32_16x16x32_bf16 v[26:29], v[224:227], v[154:157], v[26:29]
	v_mfma_f32_16x16x32_bf16 v[18:21], v[224:227], v[162:165], v[18:21]
	v_mfma_f32_16x16x32_bf16 v[18:21], v[228:231], v[166:169], v[18:21]
	v_mfma_f32_16x16x32_bf16 v[22:25], v[220:223], v[166:169], v[22:25]
	v_mfma_f32_16x16x32_bf16 v[22:25], v[186:189], v[162:165], v[22:25]
	v_mfma_f32_16x16x32_bf16 v[14:17], v[186:189], v[170:173], v[14:17]
	v_mfma_f32_16x16x32_bf16 v[14:17], v[220:223], v[174:177], v[14:17]
	v_mfma_f32_16x16x32_bf16 v[10:13], v[228:231], v[174:177], v[10:13]
	v_mfma_f32_16x16x32_bf16 v[10:13], v[224:227], v[170:173], v[10:13]
	v_mfma_f32_16x16x32_bf16 v[2:5], v[224:227], v[178:181], v[2:5]
	v_mfma_f32_16x16x32_bf16 v[2:5], v[228:231], v[182:185], v[2:5]
	v_mfma_f32_16x16x32_bf16 v[6:9], v[220:223], v[182:185], v[6:9]
	v_mfma_f32_16x16x32_bf16 v[6:9], v[186:189], v[178:181], v[6:9]
	s_add_u32 s12, s12, 0x100
	s_addc_u32 s13, s13, 0
	s_cmp_lt_i32 s34, s29
	s_barrier
	s_cbranch_scc1 .LBB0_203
	ds_read_b128 v[138:141], v137
	ds_read_b128 v[142:145], v137 offset:1024
	ds_read_b128 v[146:149], v137 offset:2048
	ds_read_b128 v[150:153], v137 offset:3072
	ds_read_b128 v[154:157], v136
	ds_read_b128 v[158:161], v136 offset:1024
	ds_read_b128 v[162:165], v136 offset:2048
	ds_read_b128 v[166:169], v136 offset:3072
	ds_read_b128 v[170:173], v136 offset:4096
	ds_read_b128 v[174:177], v136 offset:5120
	ds_read_b128 v[178:181], v136 offset:6144
	ds_read_b128 v[182:185], v136 offset:7168
	s_add_i32 s34, s37, -1
	s_lshl_b64 s[8:9], s[34:35], 7
	s_add_u32 s6, s6, s8
	s_addc_u32 s7, s7, s9
	s_mov_b32 m0, vcc_lo
	s_nop 0
	global_load_lds_dwordx4 v132, s[6:7]
	s_nop 0
	s_mov_b32 m0, s92
	s_nop 0
	global_load_lds_dwordx4 v131, s[6:7]
	s_barrier
	s_waitcnt lgkmcnt(0)
	s_waitcnt lgkmcnt(7)
	v_mfma_f32_16x16x32_bf16 v[126:129], v[138:141], v[154:157], v[126:129]
	v_mfma_f32_16x16x32_bf16 v[122:125], v[146:149], v[154:157], v[122:125]
	s_waitcnt lgkmcnt(5)
	v_mfma_f32_16x16x32_bf16 v[118:121], v[138:141], v[162:165], v[118:121]
	v_mfma_f32_16x16x32_bf16 v[114:117], v[146:149], v[162:165], v[114:117]
	s_waitcnt lgkmcnt(3)
	v_mfma_f32_16x16x32_bf16 v[110:113], v[138:141], v[170:173], v[110:113]
	s_waitcnt lgkmcnt(1)
	v_mfma_f32_16x16x32_bf16 v[102:105], v[138:141], v[178:181], v[102:105]
	v_mfma_f32_16x16x32_bf16 v[98:101], v[146:149], v[178:181], v[98:101]
	v_mfma_f32_16x16x32_bf16 v[126:129], v[142:145], v[158:161], v[126:129]
	v_mfma_f32_16x16x32_bf16 v[122:125], v[150:153], v[158:161], v[122:125]
	v_mfma_f32_16x16x32_bf16 v[118:121], v[142:145], v[166:169], v[118:121]
	v_mfma_f32_16x16x32_bf16 v[114:117], v[150:153], v[166:169], v[114:117]
	v_mfma_f32_16x16x32_bf16 v[110:113], v[142:145], v[174:177], v[110:113]
	v_mfma_f32_16x16x32_bf16 v[106:109], v[146:149], v[170:173], v[106:109]
	s_waitcnt lgkmcnt(0)
	v_mfma_f32_16x16x32_bf16 v[102:105], v[142:145], v[182:185], v[102:105]
	v_mfma_f32_16x16x32_bf16 v[98:101], v[150:153], v[182:185], v[98:101]
	v_mfma_f32_16x16x32_bf16 v[186:189], v[150:153], v[174:177], v[106:109]
	s_barrier
	s_nop 1
	ds_read_b128 v[106:109], v137 offset:16384
	ds_read_b128 v[220:223], v137 offset:17408
	ds_read_b128 v[224:227], v137 offset:18432
	ds_read_b128 v[228:231], v137 offset:19456
	s_barrier
	s_waitcnt lgkmcnt(0)
	s_waitcnt lgkmcnt(1)
	v_mfma_f32_16x16x32_bf16 v[90:93], v[224:227], v[154:157], v[90:93]
	v_mfma_f32_16x16x32_bf16 v[86:89], v[106:109], v[162:165], v[86:89]
	v_mfma_f32_16x16x32_bf16 v[82:85], v[224:227], v[162:165], v[82:85]
	v_mfma_f32_16x16x32_bf16 v[78:81], v[106:109], v[170:173], v[78:81]
	v_mfma_f32_16x16x32_bf16 v[74:77], v[224:227], v[170:173], v[74:77]
	v_mfma_f32_16x16x32_bf16 v[66:69], v[224:227], v[178:181], v[66:69]
	v_mfma_f32_16x16x32_bf16 v[94:97], v[106:109], v[154:157], v[94:97]
	s_waitcnt lgkmcnt(0)
	v_mfma_f32_16x16x32_bf16 v[90:93], v[228:231], v[158:161], v[90:93]
	v_mfma_f32_16x16x32_bf16 v[86:89], v[220:223], v[166:169], v[86:89]
	v_mfma_f32_16x16x32_bf16 v[82:85], v[228:231], v[166:169], v[82:85]
	v_mfma_f32_16x16x32_bf16 v[78:81], v[220:223], v[174:177], v[78:81]
	v_mfma_f32_16x16x32_bf16 v[74:77], v[228:231], v[174:177], v[74:77]
	v_mfma_f32_16x16x32_bf16 v[70:73], v[106:109], v[178:181], v[70:73]
	v_mfma_f32_16x16x32_bf16 v[66:69], v[228:231], v[182:185], v[66:69]
	v_mfma_f32_16x16x32_bf16 v[232:235], v[220:223], v[158:161], v[94:97]
	v_mfma_f32_16x16x32_bf16 v[154:157], v[220:223], v[182:185], v[70:73]
	s_barrier
; #define WAIT_V(n) asm volatile("s_waitcnt vmcnt(" #n ")" ::: "memory")
; #define WAIT_L(n) asm volatile("s_waitcnt lgkmcnt(" #n ")" ::: "memory")
; #define BAR __builtin_amdgcn_s_barrier()
; #define LDA(dst, b, h)                                                                                   \
;   _Pragma("unroll") for (int m = 0; m < 4; ++m) _Pragma("unroll") for (int k = 0; k < 2; ++k) dst[m][k] = \
;       *reinterpret_cast<const bf16x8*>(aRd + ((b) * 2 + (h)) * 16384 + m * 2048 + k * 1024)
; #define LDB(dst, b, h)                                                                                   \
;   _Pragma("unroll") for (int n = 0; n < 2; ++n) _Pragma("unroll") for (int k = 0; k < 2; ++k) dst[n][k] = \
;       *reinterpret_cast<const bf16x8*>(bRd + ((b) * 2 + (h)) * 16384 + n * 2048 + k * 1024)
; template <int EPI> ...
;     ...
;     LDA(At, 0, 1);
;     WAIT_V(4);
;     BAR;
;     WAIT_L(0);
;     MMA(1, 0, At, B0);
;     MMA(1, 1, At, B1);
;     BAR;
;   }
;   {
;     LDB(B0, 1, 0);
;     LDA(At, 1, 0);
;     WAIT_V(2);
;     BAR;
;     WAIT_L(0);
;     MMA(0, 0, At, B0);
	s_nop 2
	ds_read_b128 v[70:73], v136 offset:16384
	ds_read_b128 v[94:97], v136 offset:17408
	ds_read_b128 v[158:161], v136 offset:18432
	ds_read_b128 v[162:165], v136 offset:19456
	ds_read_b128 v[166:169], v136 offset:20480
	ds_read_b128 v[170:173], v136 offset:21504
	ds_read_b128 v[174:177], v136 offset:22528
	ds_read_b128 v[178:181], v136 offset:23552
	s_waitcnt vmcnt(4)
	s_barrier
	s_waitcnt lgkmcnt(0)
	s_waitcnt lgkmcnt(7)
	v_mfma_f32_16x16x32_bf16 v[62:65], v[138:141], v[70:73], v[62:65]
	s_waitcnt lgkmcnt(5)
	v_mfma_f32_16x16x32_bf16 v[54:57], v[138:141], v[158:161], v[54:57]
	v_mfma_f32_16x16x32_bf16 v[50:53], v[146:149], v[158:161], v[50:53]
	s_waitcnt lgkmcnt(1)
	v_mfma_f32_16x16x32_bf16 v[38:41], v[138:141], v[174:177], v[38:41]
	v_mfma_f32_16x16x32_bf16 v[62:65], v[142:145], v[94:97], v[62:65]
	v_mfma_f32_16x16x32_bf16 v[58:61], v[146:149], v[70:73], v[58:61]
	v_mfma_f32_16x16x32_bf16 v[54:57], v[142:145], v[162:165], v[54:57]
	v_mfma_f32_16x16x32_bf16 v[50:53], v[150:153], v[162:165], v[50:53]
	v_mfma_f32_16x16x32_bf16 v[46:49], v[138:141], v[166:169], v[46:49]
	v_mfma_f32_16x16x32_bf16 v[42:45], v[146:149], v[166:169], v[42:45]
	s_waitcnt lgkmcnt(0)
	v_mfma_f32_16x16x32_bf16 v[38:41], v[142:145], v[178:181], v[38:41]
	v_mfma_f32_16x16x32_bf16 v[34:37], v[146:149], v[174:177], v[34:37]
	v_mfma_f32_16x16x32_bf16 v[182:185], v[150:153], v[94:97], v[58:61]
	v_mfma_f32_16x16x32_bf16 v[236:239], v[142:145], v[170:173], v[46:49]
	v_mfma_f32_16x16x32_bf16 v[240:243], v[150:153], v[170:173], v[42:45]
	v_mfma_f32_16x16x32_bf16 v[138:141], v[150:153], v[178:181], v[34:37]
	v_mfma_f32_16x16x32_bf16 v[30:33], v[106:109], v[70:73], v[30:33]
	v_mfma_f32_16x16x32_bf16 v[26:29], v[224:227], v[70:73], v[26:29]
	v_mfma_f32_16x16x32_bf16 v[22:25], v[106:109], v[158:161], v[22:25]
	v_mfma_f32_16x16x32_bf16 v[18:21], v[224:227], v[158:161], v[18:21]
	v_mfma_f32_16x16x32_bf16 v[14:17], v[106:109], v[166:169], v[14:17]
	v_mfma_f32_16x16x32_bf16 v[10:13], v[224:227], v[166:169], v[10:13]
	v_mfma_f32_16x16x32_bf16 v[6:9], v[106:109], v[174:177], v[6:9]
	v_mfma_f32_16x16x32_bf16 v[2:5], v[224:227], v[174:177], v[2:5]
	v_mfma_f32_16x16x32_bf16 v[142:145], v[220:223], v[94:97], v[30:33]
	v_mfma_f32_16x16x32_bf16 v[146:149], v[228:231], v[94:97], v[26:29]
	v_mfma_f32_16x16x32_bf16 v[150:153], v[220:223], v[162:165], v[22:25]
	v_mfma_f32_16x16x32_bf16 v[158:161], v[228:231], v[162:165], v[18:21]
	v_mfma_f32_16x16x32_bf16 v[162:165], v[220:223], v[170:173], v[14:17]
	v_mfma_f32_16x16x32_bf16 v[166:169], v[228:231], v[170:173], v[10:13]
	v_mfma_f32_16x16x32_bf16 v[170:173], v[220:223], v[178:181], v[6:9]
	v_mfma_f32_16x16x32_bf16 v[174:177], v[228:231], v[178:181], v[2:5]
	s_barrier
	ds_read_b128 v[18:21], v137 offset:32768
	ds_read_b128 v[22:25], v137 offset:33792
	ds_read_b128 v[26:29], v137 offset:34816
	ds_read_b128 v[178:181], v137 offset:35840
	ds_read_b128 v[46:49], v136 offset:32768
	ds_read_b128 v[58:61], v136 offset:33792
	ds_read_b128 v[70:73], v136 offset:34816
	ds_read_b128 v[220:223], v136 offset:35840
	ds_read_b128 v[224:227], v136 offset:36864
	ds_read_b128 v[228:231], v136 offset:37888
	ds_read_b128 v[244:247], v136 offset:38912
	ds_read_b128 v[248:251], v136 offset:39936
	s_waitcnt vmcnt(2)
	s_barrier
	s_waitcnt lgkmcnt(0)
	s_waitcnt lgkmcnt(7)
	v_mfma_f32_16x16x32_bf16 v[2:5], v[18:21], v[46:49], v[126:129]
	s_waitcnt lgkmcnt(6)
	v_mfma_f32_16x16x32_bf16 v[94:97], v[22:25], v[58:61], v[2:5]
	v_mfma_f32_16x16x32_bf16 v[2:5], v[26:29], v[46:49], v[122:125]
	v_mfma_f32_16x16x32_bf16 v[106:109], v[178:181], v[58:61], v[2:5]
	s_waitcnt lgkmcnt(5)
	v_mfma_f32_16x16x32_bf16 v[2:5], v[18:21], v[70:73], v[118:121]
	s_waitcnt lgkmcnt(4)
	v_mfma_f32_16x16x32_bf16 v[30:33], v[22:25], v[220:223], v[2:5]
	v_mfma_f32_16x16x32_bf16 v[2:5], v[26:29], v[70:73], v[114:117]
	v_mfma_f32_16x16x32_bf16 v[42:45], v[178:181], v[220:223], v[2:5]
	s_waitcnt lgkmcnt(3)
	v_mfma_f32_16x16x32_bf16 v[2:5], v[18:21], v[224:227], v[110:113]
	s_waitcnt lgkmcnt(2)
	v_mfma_f32_16x16x32_bf16 v[10:13], v[22:25], v[228:231], v[2:5]
	v_mfma_f32_16x16x32_bf16 v[2:5], v[26:29], v[224:227], v[186:189]
	v_mfma_f32_16x16x32_bf16 v[14:17], v[178:181], v[228:231], v[2:5]
	s_waitcnt lgkmcnt(1)
	v_mfma_f32_16x16x32_bf16 v[2:5], v[18:21], v[244:247], v[102:105]
	v_mfma_f32_16x16x32_bf16 v[6:9], v[26:29], v[244:247], v[98:101]
	s_waitcnt lgkmcnt(0)
	v_mfma_f32_16x16x32_bf16 v[2:5], v[22:25], v[248:251], v[2:5]
	v_mfma_f32_16x16x32_bf16 v[6:9], v[178:181], v[248:251], v[6:9]
	s_barrier
; #define WAIT_V(n) asm volatile("s_waitcnt vmcnt(" #n ")" ::: "memory")
; #define WAIT_L(n) asm volatile("s_waitcnt lgkmcnt(" #n ")" ::: "memory")
; #define BAR __builtin_amdgcn_s_barrier()
; #define LDA(dst, b, h)                                                                                   \
;   _Pragma("unroll") for (int m = 0; m < 4; ++m) _Pragma("unroll") for (int k = 0; k < 2; ++k) dst[m][k] = \
;       *reinterpret_cast<const bf16x8*>(aRd + ((b) * 2 + (h)) * 16384 + m * 2048 + k * 1024)
; #define LDB(dst, b, h)                                                                                   \
;   _Pragma("unroll") for (int n = 0; n < 2; ++n) _Pragma("unroll") for (int k = 0; k < 2; ++k) dst[n][k] = \
;       *reinterpret_cast<const bf16x8*>(bRd + ((b) * 2 + (h)) * 16384 + n * 2048 + k * 1024)
; template <int EPI> ...
;     ...
;     LDB(B1, 1, 1);
;     WAIT_V(0);
;     BAR;
;     WAIT_L(0);
;     MMA(0, 1, At, B1);
;     BAR;
;     LDA(At, 1, 1);
;     BAR;
;     WAIT_L(0);
;     MMA(1, 0, At, B0);
;     MMA(1, 1, At, B1);
;     BAR;
;   }
;   if (wr == 0) BAR;
	ds_read_b128 v[102:105], v137 offset:49152
	ds_read_b128 v[186:189], v137 offset:50176
	ds_read_b128 v[196:199], v137 offset:51200
	ds_read_b128 v[212:215], v137 offset:52224
	s_waitcnt vmcnt(0)
	s_barrier
	s_waitcnt lgkmcnt(0)
	s_waitcnt lgkmcnt(3)
	v_mfma_f32_16x16x32_bf16 v[34:37], v[102:105], v[46:49], v[232:235]
	s_waitcnt lgkmcnt(1)
	v_mfma_f32_16x16x32_bf16 v[46:49], v[196:199], v[46:49], v[90:93]
	v_mfma_f32_16x16x32_bf16 v[74:77], v[196:199], v[224:227], v[74:77]
	v_mfma_f32_16x16x32_bf16 v[34:37], v[186:189], v[58:61], v[34:37]
	s_waitcnt lgkmcnt(0)
	v_mfma_f32_16x16x32_bf16 v[46:49], v[212:215], v[58:61], v[46:49]
	v_mfma_f32_16x16x32_bf16 v[58:61], v[102:105], v[70:73], v[86:89]
	v_mfma_f32_16x16x32_bf16 v[70:73], v[196:199], v[70:73], v[82:85]
	v_mfma_f32_16x16x32_bf16 v[78:81], v[102:105], v[224:227], v[78:81]
	v_mfma_f32_16x16x32_bf16 v[86:89], v[212:215], v[228:231], v[74:77]
	v_mfma_f32_16x16x32_bf16 v[74:77], v[102:105], v[244:247], v[154:157]
	v_mfma_f32_16x16x32_bf16 v[66:69], v[196:199], v[244:247], v[66:69]
	v_mfma_f32_16x16x32_bf16 v[58:61], v[186:189], v[220:223], v[58:61]
	v_mfma_f32_16x16x32_bf16 v[70:73], v[212:215], v[220:223], v[70:73]
	v_mfma_f32_16x16x32_bf16 v[78:81], v[186:189], v[228:231], v[78:81]
	v_mfma_f32_16x16x32_bf16 v[98:101], v[186:189], v[248:251], v[74:77]
	v_mfma_f32_16x16x32_bf16 v[110:113], v[212:215], v[248:251], v[66:69]
	s_barrier
	s_nop 0
	ds_read_b128 v[66:69], v136 offset:49152
	ds_read_b128 v[74:77], v136 offset:50176
	ds_read_b128 v[82:85], v136 offset:51200
	ds_read_b128 v[90:93], v136 offset:52224
	ds_read_b128 v[154:157], v136 offset:53248
	ds_read_b128 v[220:223], v136 offset:54272
	ds_read_b128 v[224:227], v136 offset:55296
	ds_read_b128 v[228:231], v136 offset:56320
	s_barrier
	s_waitcnt lgkmcnt(0)
	s_waitcnt lgkmcnt(5)
	v_mfma_f32_16x16x32_bf16 v[50:53], v[26:29], v[82:85], v[50:53]
	v_mfma_f32_16x16x32_bf16 v[62:65], v[18:21], v[66:69], v[62:65]
	v_mfma_f32_16x16x32_bf16 v[54:57], v[18:21], v[82:85], v[54:57]
	s_waitcnt lgkmcnt(4)
	v_mfma_f32_16x16x32_bf16 v[118:121], v[178:181], v[90:93], v[50:53]
	s_waitcnt lgkmcnt(3)
	v_mfma_f32_16x16x32_bf16 v[50:53], v[18:21], v[154:157], v[236:239]
	s_waitcnt lgkmcnt(1)
	v_mfma_f32_16x16x32_bf16 v[18:21], v[18:21], v[224:227], v[38:41]
	v_mfma_f32_16x16x32_bf16 v[122:125], v[22:25], v[74:77], v[62:65]
	v_mfma_f32_16x16x32_bf16 v[62:65], v[26:29], v[66:69], v[182:185]
	v_mfma_f32_16x16x32_bf16 v[114:117], v[22:25], v[90:93], v[54:57]
	v_mfma_f32_16x16x32_bf16 v[50:53], v[22:25], v[220:223], v[50:53]
	v_mfma_f32_16x16x32_bf16 v[54:57], v[26:29], v[154:157], v[240:243]
	s_waitcnt lgkmcnt(0)
	v_mfma_f32_16x16x32_bf16 v[18:21], v[22:25], v[228:231], v[18:21]
	v_mfma_f32_16x16x32_bf16 v[22:25], v[26:29], v[224:227], v[138:141]
	v_mfma_f32_16x16x32_bf16 v[126:129], v[178:181], v[74:77], v[62:65]
	v_mfma_f32_16x16x32_bf16 v[62:65], v[178:181], v[220:223], v[54:57]
	v_mfma_f32_16x16x32_bf16 v[22:25], v[178:181], v[228:231], v[22:25]
	v_mfma_f32_16x16x32_bf16 v[26:29], v[102:105], v[66:69], v[142:145]
	v_mfma_f32_16x16x32_bf16 v[38:41], v[196:199], v[66:69], v[146:149]
	v_mfma_f32_16x16x32_bf16 v[54:57], v[102:105], v[82:85], v[150:153]
	v_mfma_f32_16x16x32_bf16 v[66:69], v[196:199], v[82:85], v[158:161]
	v_mfma_f32_16x16x32_bf16 v[26:29], v[186:189], v[74:77], v[26:29]
	v_mfma_f32_16x16x32_bf16 v[38:41], v[212:215], v[74:77], v[38:41]
	v_mfma_f32_16x16x32_bf16 v[54:57], v[186:189], v[90:93], v[54:57]
	v_mfma_f32_16x16x32_bf16 v[66:69], v[212:215], v[90:93], v[66:69]
	v_mfma_f32_16x16x32_bf16 v[74:77], v[102:105], v[154:157], v[162:165]
	v_mfma_f32_16x16x32_bf16 v[82:85], v[196:199], v[154:157], v[166:169]
	v_mfma_f32_16x16x32_bf16 v[90:93], v[102:105], v[224:227], v[170:173]
	v_mfma_f32_16x16x32_bf16 v[102:105], v[196:199], v[224:227], v[174:177]
	v_mfma_f32_16x16x32_bf16 v[74:77], v[186:189], v[220:223], v[74:77]
	v_mfma_f32_16x16x32_bf16 v[82:85], v[212:215], v[220:223], v[82:85]
	v_mfma_f32_16x16x32_bf16 v[90:93], v[186:189], v[228:231], v[90:93]
	v_mfma_f32_16x16x32_bf16 v[102:105], v[212:215], v[228:231], v[102:105]
	s_movk_i32 s6, 0x100
	v_cmp_gt_u32_e32 vcc, s6, v133
	s_barrier
	s_and_saveexec_b64 s[12:13], vcc
	s_cbranch_execz .LBB0_206
	s_barrier

; #define WAIT_V(n) asm volatile("s_waitcnt vmcnt(" #n ")" ::: "memory")
; #define WAIT_L(n) asm volatile("s_waitcnt lgkmcnt(" #n ")" ::: "memory")
; #define BAR __builtin_amdgcn_s_barrier()
; #define SCHED __builtin_amdgcn_sched_barrier(0)
; #define STAGE_A(b, h, kt)                                        \
;   do {                                                           \
;     const char* _g = Ab + (h) * halfK + (long)(kt) * 128;        \
;     GLDS2(_g, (unsigned)(((b) * 2 + (h)) * 16384));              \
;   } while (0)
; #define STAGE_B(b, h, kt)                                        \
;   do {                                                           \
;     const char* _g = Bb + (h) * halfK + (long)(kt) * 128;        \
;     GLDS2(_g, (unsigned)(65536 + ((b) * 2 + (h)) * 16384));      \
;   } while (0)
; #define LDA(dst, b, h)                                                                                   \
;   _Pragma("unroll") for (int m = 0; m < 4; ++m) _Pragma("unroll") for (int k = 0; k < 2; ++k) dst[m][k] = \
;       *reinterpret_cast<const bf16x8*>(aRd + ((b) * 2 + (h)) * 16384 + m * 2048 + k * 1024)
; #define LDB(dst, b, h)                                                                                   \
;   _Pragma("unroll") for (int n = 0; n < 2; ++n) _Pragma("unroll") for (int k = 0; k < 2; ++k) dst[n][k] = \
;       *reinterpret_cast<const bf16x8*>(bRd + ((b) * 2 + (h)) * 16384 + n * 2048 + k * 1024)
; template <int EPI> ...
;     ...
;   for (int t = 0; t < nt - 2; t += 2) {
;     LDB(B0, 0, 0);
;     SCHED;
;     LDA(At, 0, 0);
;     STAGE_A(1, 1, t + 1);
;     WAIT_L(8);
;     BAR;
;     WAIT_L(0);
;     MMA(0, 0, At, B0);
;     BAR;
;     SCHED;
;     LDB(B1, 0, 1);
;     STAGE_B(0, 0, t + 2);
;     BAR;
;     WAIT_L(0);
;     MMA(0, 1, At, B1);
;     BAR;
;     LDA(At, 0, 1);
;     STAGE_A(0, 0, t + 2);
;     BAR;
;     WAIT_L(0);
;     MMA(1, 0, At, B0);
;     BAR;
;     SCHED;
;     STAGE_B(0, 1, t + 2);
;     WAIT_V(6);
;     BAR;
;     MMA(1, 1, At, B1);
.LBB0_415:
	ds_read_b128 v[138:141], v136
	ds_read_b128 v[142:145], v136 offset:1024
	ds_read_b128 v[146:149], v136 offset:2048
	ds_read_b128 v[150:153], v136 offset:3072
	ds_read_b128 v[154:157], v135
	ds_read_b128 v[158:161], v135 offset:1024
	ds_read_b128 v[162:165], v135 offset:2048
	ds_read_b128 v[170:173], v135 offset:3072
	ds_read_b128 v[174:177], v135 offset:4096
	ds_read_b128 v[178:181], v135 offset:5120
	ds_read_b128 v[182:185], v135 offset:6144
	ds_read_b128 v[186:189], v135 offset:7168
	s_add_u32 s64, s10, s12
	s_addc_u32 s78, s11, s13
	s_add_u32 s74, s64, 0x80
	s_addc_u32 s75, s78, 0
	s_mov_b32 m0, s62
	s_nop 0
	global_load_lds_dwordx4 v132, s[74:75]
	s_nop 0
	s_mov_b32 m0, s59
	s_nop 0
	global_load_lds_dwordx4 v131, s[74:75]
	s_waitcnt lgkmcnt(8)
	s_barrier
	s_waitcnt lgkmcnt(0)
	v_mfma_f32_16x16x32_bf16 v[126:129], v[138:141], v[154:157], v[126:129]
	v_mfma_f32_16x16x32_bf16 v[126:129], v[142:145], v[158:161], v[126:129]
	v_mfma_f32_16x16x32_bf16 v[122:125], v[150:153], v[158:161], v[122:125]
	v_mfma_f32_16x16x32_bf16 v[122:125], v[146:149], v[154:157], v[122:125]
	v_mfma_f32_16x16x32_bf16 v[114:117], v[146:149], v[162:165], v[114:117]
	v_mfma_f32_16x16x32_bf16 v[114:117], v[150:153], v[170:173], v[114:117]
	v_mfma_f32_16x16x32_bf16 v[118:121], v[142:145], v[170:173], v[118:121]
	v_mfma_f32_16x16x32_bf16 v[118:121], v[138:141], v[162:165], v[118:121]
	v_mfma_f32_16x16x32_bf16 v[110:113], v[138:141], v[174:177], v[110:113]
	v_mfma_f32_16x16x32_bf16 v[110:113], v[142:145], v[178:181], v[110:113]
	v_mfma_f32_16x16x32_bf16 v[106:109], v[150:153], v[178:181], v[106:109]
	v_mfma_f32_16x16x32_bf16 v[106:109], v[146:149], v[174:177], v[106:109]
	v_mfma_f32_16x16x32_bf16 v[98:101], v[146:149], v[182:185], v[98:101]
	v_mfma_f32_16x16x32_bf16 v[98:101], v[150:153], v[186:189], v[98:101]
	v_mfma_f32_16x16x32_bf16 v[102:105], v[142:145], v[186:189], v[102:105]
	v_mfma_f32_16x16x32_bf16 v[102:105], v[138:141], v[182:185], v[102:105]
	s_barrier
	ds_read_b128 v[220:223], v136 offset:16384
	ds_read_b128 v[224:227], v136 offset:17408
	ds_read_b128 v[228:231], v136 offset:18432
	ds_read_b128 v[232:235], v136 offset:19456
	s_add_u32 s79, s72, s12
	s_addc_u32 s80, s73, s13
	s_add_u32 s74, s79, 0x100
	s_addc_u32 s75, s80, 0
	s_mov_b32 m0, s15
	s_nop 0
	global_load_lds_dwordx4 v132, s[74:75]
	s_nop 0
	s_mov_b32 m0, s33
	s_nop 0
	global_load_lds_dwordx4 v131, s[74:75]
	s_barrier
	s_waitcnt lgkmcnt(0)
	v_mfma_f32_16x16x32_bf16 v[94:97], v[220:223], v[154:157], v[94:97]
	v_mfma_f32_16x16x32_bf16 v[94:97], v[224:227], v[158:161], v[94:97]
	v_mfma_f32_16x16x32_bf16 v[90:93], v[232:235], v[158:161], v[90:93]
	v_mfma_f32_16x16x32_bf16 v[90:93], v[228:231], v[154:157], v[90:93]
	v_mfma_f32_16x16x32_bf16 v[82:85], v[228:231], v[162:165], v[82:85]
	v_mfma_f32_16x16x32_bf16 v[82:85], v[232:235], v[170:173], v[82:85]
	v_mfma_f32_16x16x32_bf16 v[86:89], v[224:227], v[170:173], v[86:89]
	v_mfma_f32_16x16x32_bf16 v[86:89], v[220:223], v[162:165], v[86:89]
	v_mfma_f32_16x16x32_bf16 v[78:81], v[220:223], v[174:177], v[78:81]
	v_mfma_f32_16x16x32_bf16 v[78:81], v[224:227], v[178:181], v[78:81]
	v_mfma_f32_16x16x32_bf16 v[74:77], v[232:235], v[178:181], v[74:77]
	v_mfma_f32_16x16x32_bf16 v[74:77], v[228:231], v[174:177], v[74:77]
	v_mfma_f32_16x16x32_bf16 v[66:69], v[228:231], v[182:185], v[66:69]
	v_mfma_f32_16x16x32_bf16 v[66:69], v[232:235], v[186:189], v[66:69]
	v_mfma_f32_16x16x32_bf16 v[70:73], v[224:227], v[186:189], v[70:73]
	v_mfma_f32_16x16x32_bf16 v[70:73], v[220:223], v[182:185], v[70:73]
	s_barrier
	ds_read_b128 v[154:157], v135 offset:16384
	ds_read_b128 v[158:161], v135 offset:17408
	ds_read_b128 v[162:165], v135 offset:18432
	ds_read_b128 v[170:173], v135 offset:19456
	ds_read_b128 v[174:177], v135 offset:20480
	ds_read_b128 v[178:181], v135 offset:21504
	ds_read_b128 v[182:185], v135 offset:22528
	ds_read_b128 v[186:189], v135 offset:23552
	s_add_u32 s81, s18, s12
	s_addc_u32 s82, s19, s13
	s_add_u32 s74, s81, 0x100
	s_addc_u32 s75, s82, 0
	s_mov_b32 m0, s2
	s_nop 0
	global_load_lds_dwordx4 v132, s[74:75]
	s_nop 0
	s_mov_b32 m0, s41
	s_nop 0
	global_load_lds_dwordx4 v131, s[74:75]
	s_barrier
	s_waitcnt lgkmcnt(0)
	v_mfma_f32_16x16x32_bf16 v[62:65], v[138:141], v[154:157], v[62:65]
	v_mfma_f32_16x16x32_bf16 v[62:65], v[142:145], v[158:161], v[62:65]
	v_mfma_f32_16x16x32_bf16 v[58:61], v[150:153], v[158:161], v[58:61]
	v_mfma_f32_16x16x32_bf16 v[58:61], v[146:149], v[154:157], v[58:61]
	v_mfma_f32_16x16x32_bf16 v[50:53], v[146:149], v[162:165], v[50:53]
	v_mfma_f32_16x16x32_bf16 v[50:53], v[150:153], v[170:173], v[50:53]
	v_mfma_f32_16x16x32_bf16 v[54:57], v[142:145], v[170:173], v[54:57]
	v_mfma_f32_16x16x32_bf16 v[54:57], v[138:141], v[162:165], v[54:57]
	v_mfma_f32_16x16x32_bf16 v[46:49], v[138:141], v[174:177], v[46:49]
	v_mfma_f32_16x16x32_bf16 v[46:49], v[142:145], v[178:181], v[46:49]
	v_mfma_f32_16x16x32_bf16 v[42:45], v[150:153], v[178:181], v[42:45]
	v_mfma_f32_16x16x32_bf16 v[42:45], v[146:149], v[174:177], v[42:45]
	v_mfma_f32_16x16x32_bf16 v[34:37], v[146:149], v[182:185], v[34:37]
	v_mfma_f32_16x16x32_bf16 v[34:37], v[150:153], v[186:189], v[34:37]
	v_mfma_f32_16x16x32_bf16 v[38:41], v[142:145], v[186:189], v[38:41]
	v_mfma_f32_16x16x32_bf16 v[38:41], v[138:141], v[182:185], v[38:41]
	s_barrier
	s_add_u32 s83, s6, s12
	s_addc_u32 s84, s7, s13
	s_add_u32 s74, s83, 0x100
	s_addc_u32 s75, s84, 0
	s_mov_b32 m0, s38
	s_nop 0
	global_load_lds_dwordx4 v132, s[74:75]
	s_nop 0
	s_mov_b32 m0, s39
	s_nop 0
	global_load_lds_dwordx4 v131, s[74:75]
	s_waitcnt vmcnt(6)
	s_barrier
; #define WAIT_L(n) asm volatile("s_waitcnt lgkmcnt(" #n ")" ::: "memory")
; #define BAR __builtin_amdgcn_s_barrier()
; #define SCHED __builtin_amdgcn_sched_barrier(0)
; #define STAGE_A(b, h, kt)                                        \
;   do {                                                           \
;     const char* _g = Ab + (h) * halfK + (long)(kt) * 128;        \
;     GLDS2(_g, (unsigned)(((b) * 2 + (h)) * 16384));              \
;   } while (0)
; #define STAGE_B(b, h, kt)                                        \
;   do {                                                           \
;     const char* _g = Bb + (h) * halfK + (long)(kt) * 128;        \
;     GLDS2(_g, (unsigned)(65536 + ((b) * 2 + (h)) * 16384));      \
;   } while (0)
; #define LDA(dst, b, h)                                                                                   \
;   _Pragma("unroll") for (int m = 0; m < 4; ++m) _Pragma("unroll") for (int k = 0; k < 2; ++k) dst[m][k] = \
;       *reinterpret_cast<const bf16x8*>(aRd + ((b) * 2 + (h)) * 16384 + m * 2048 + k * 1024)
; #define LDB(dst, b, h)                                                                                   \
;   _Pragma("unroll") for (int n = 0; n < 2; ++n) _Pragma("unroll") for (int k = 0; k < 2; ++k) dst[n][k] = \
;       *reinterpret_cast<const bf16x8*>(bRd + ((b) * 2 + (h)) * 16384 + n * 2048 + k * 1024)
; template <int EPI> ...
;     ...
;     MMA(1, 1, At, B1);
;     BAR;
;     LDB(B0, 1, 0);
;     SCHED;
;     LDA(At, 1, 0);
;     STAGE_A(0, 1, t + 2);
;     WAIT_L(8);
;     BAR;
;     WAIT_L(0);
;     MMA(0, 0, At, B0);
;     BAR;
;     SCHED;
;     LDB(B1, 1, 1);
;     STAGE_B(1, 0, t + 3);
;     BAR;
;     WAIT_L(0);
;     MMA(0, 1, At, B1);
;     BAR;
;     LDA(At, 1, 1);
;     STAGE_A(1, 0, t + 3);
;     BAR;
;     WAIT_L(0);
;     MMA(1, 0, At, B0);
;     BAR;
;     SCHED;
;     STAGE_B(1, 1, t + 3);
	v_mfma_f32_16x16x32_bf16 v[30:33], v[220:223], v[154:157], v[30:33]
	v_mfma_f32_16x16x32_bf16 v[30:33], v[224:227], v[158:161], v[30:33]
	v_mfma_f32_16x16x32_bf16 v[26:29], v[232:235], v[158:161], v[26:29]
	v_mfma_f32_16x16x32_bf16 v[26:29], v[228:231], v[154:157], v[26:29]
	v_mfma_f32_16x16x32_bf16 v[18:21], v[228:231], v[162:165], v[18:21]
	v_mfma_f32_16x16x32_bf16 v[18:21], v[232:235], v[170:173], v[18:21]
	v_mfma_f32_16x16x32_bf16 v[22:25], v[224:227], v[170:173], v[22:25]
	v_mfma_f32_16x16x32_bf16 v[22:25], v[220:223], v[162:165], v[22:25]
	v_mfma_f32_16x16x32_bf16 v[14:17], v[220:223], v[174:177], v[14:17]
	v_mfma_f32_16x16x32_bf16 v[14:17], v[224:227], v[178:181], v[14:17]
	v_mfma_f32_16x16x32_bf16 v[10:13], v[232:235], v[178:181], v[10:13]
	v_mfma_f32_16x16x32_bf16 v[10:13], v[228:231], v[174:177], v[10:13]
	v_mfma_f32_16x16x32_bf16 v[2:5], v[228:231], v[182:185], v[2:5]
	v_mfma_f32_16x16x32_bf16 v[2:5], v[232:235], v[186:189], v[2:5]
	v_mfma_f32_16x16x32_bf16 v[6:9], v[224:227], v[186:189], v[6:9]
	v_mfma_f32_16x16x32_bf16 v[6:9], v[220:223], v[182:185], v[6:9]
	s_barrier
	ds_read_b128 v[138:141], v136 offset:32768
	ds_read_b128 v[142:145], v136 offset:33792
	ds_read_b128 v[146:149], v136 offset:34816
	ds_read_b128 v[150:153], v136 offset:35840
	ds_read_b128 v[154:157], v135 offset:32768
	ds_read_b128 v[158:161], v135 offset:33792
	ds_read_b128 v[162:165], v135 offset:34816
	ds_read_b128 v[170:173], v135 offset:35840
	ds_read_b128 v[174:177], v135 offset:36864
	ds_read_b128 v[178:181], v135 offset:37888
	ds_read_b128 v[182:185], v135 offset:38912
	ds_read_b128 v[186:189], v135 offset:39936
	s_add_u32 s74, s64, 0x100
	s_addc_u32 s75, s78, 0
	s_mov_b32 m0, s47
	s_nop 0
	global_load_lds_dwordx4 v132, s[74:75]
	s_nop 0
	s_mov_b32 m0, s48
	s_nop 0
	global_load_lds_dwordx4 v131, s[74:75]
	s_waitcnt lgkmcnt(8)
	s_barrier
	s_waitcnt lgkmcnt(0)
	v_mfma_f32_16x16x32_bf16 v[126:129], v[138:141], v[154:157], v[126:129]
	v_mfma_f32_16x16x32_bf16 v[126:129], v[142:145], v[158:161], v[126:129]
	v_mfma_f32_16x16x32_bf16 v[122:125], v[150:153], v[158:161], v[122:125]
	v_mfma_f32_16x16x32_bf16 v[122:125], v[146:149], v[154:157], v[122:125]
	v_mfma_f32_16x16x32_bf16 v[114:117], v[146:149], v[162:165], v[114:117]
	v_mfma_f32_16x16x32_bf16 v[114:117], v[150:153], v[170:173], v[114:117]
	v_mfma_f32_16x16x32_bf16 v[118:121], v[142:145], v[170:173], v[118:121]
	v_mfma_f32_16x16x32_bf16 v[118:121], v[138:141], v[162:165], v[118:121]
	v_mfma_f32_16x16x32_bf16 v[110:113], v[138:141], v[174:177], v[110:113]
	v_mfma_f32_16x16x32_bf16 v[110:113], v[142:145], v[178:181], v[110:113]
	v_mfma_f32_16x16x32_bf16 v[106:109], v[150:153], v[178:181], v[106:109]
	v_mfma_f32_16x16x32_bf16 v[106:109], v[146:149], v[174:177], v[106:109]
	v_mfma_f32_16x16x32_bf16 v[98:101], v[146:149], v[182:185], v[98:101]
	v_mfma_f32_16x16x32_bf16 v[98:101], v[150:153], v[186:189], v[98:101]
	v_mfma_f32_16x16x32_bf16 v[102:105], v[142:145], v[186:189], v[102:105]
	v_mfma_f32_16x16x32_bf16 v[102:105], v[138:141], v[182:185], v[102:105]
	s_barrier
	ds_read_b128 v[220:223], v136 offset:49152
	ds_read_b128 v[224:227], v136 offset:50176
	ds_read_b128 v[228:231], v136 offset:51200
	ds_read_b128 v[232:235], v136 offset:52224
	s_add_u32 s74, s79, 0x180
	s_addc_u32 s75, s80, 0
	s_mov_b32 m0, s50
	s_nop 0
	global_load_lds_dwordx4 v132, s[74:75]
	s_nop 0
	s_mov_b32 m0, s51
	s_nop 0
	global_load_lds_dwordx4 v131, s[74:75]
	s_barrier
	s_waitcnt lgkmcnt(0)
	v_mfma_f32_16x16x32_bf16 v[94:97], v[220:223], v[154:157], v[94:97]
	v_mfma_f32_16x16x32_bf16 v[94:97], v[224:227], v[158:161], v[94:97]
	v_mfma_f32_16x16x32_bf16 v[90:93], v[232:235], v[158:161], v[90:93]
	v_mfma_f32_16x16x32_bf16 v[90:93], v[228:231], v[154:157], v[90:93]
	v_mfma_f32_16x16x32_bf16 v[82:85], v[228:231], v[162:165], v[82:85]
	v_mfma_f32_16x16x32_bf16 v[82:85], v[232:235], v[170:173], v[82:85]
	v_mfma_f32_16x16x32_bf16 v[86:89], v[224:227], v[170:173], v[86:89]
	v_mfma_f32_16x16x32_bf16 v[86:89], v[220:223], v[162:165], v[86:89]
	v_mfma_f32_16x16x32_bf16 v[78:81], v[220:223], v[174:177], v[78:81]
	v_mfma_f32_16x16x32_bf16 v[78:81], v[224:227], v[178:181], v[78:81]
	v_mfma_f32_16x16x32_bf16 v[74:77], v[232:235], v[178:181], v[74:77]
	v_mfma_f32_16x16x32_bf16 v[74:77], v[228:231], v[174:177], v[74:77]
	v_mfma_f32_16x16x32_bf16 v[66:69], v[228:231], v[182:185], v[66:69]
	v_mfma_f32_16x16x32_bf16 v[66:69], v[232:235], v[186:189], v[66:69]
	v_mfma_f32_16x16x32_bf16 v[70:73], v[224:227], v[186:189], v[70:73]
	v_mfma_f32_16x16x32_bf16 v[70:73], v[220:223], v[182:185], v[70:73]
	s_barrier
	ds_read_b128 v[154:157], v135 offset:49152
	ds_read_b128 v[158:161], v135 offset:50176
	ds_read_b128 v[162:165], v135 offset:51200
	ds_read_b128 v[170:173], v135 offset:52224
	ds_read_b128 v[174:177], v135 offset:53248
	ds_read_b128 v[178:181], v135 offset:54272
	ds_read_b128 v[182:185], v135 offset:55296
	ds_read_b128 v[186:189], v135 offset:56320
	s_add_u32 s74, s81, 0x180
	s_addc_u32 s75, s82, 0
	s_mov_b32 m0, s58
	s_nop 0
	global_load_lds_dwordx4 v132, s[74:75]
	s_nop 0
	s_mov_b32 m0, s63
	s_nop 0
	global_load_lds_dwordx4 v131, s[74:75]
	s_barrier
; #define WAIT_V(n) asm volatile("s_waitcnt vmcnt(" #n ")" ::: "memory")
; #define WAIT_L(n) asm volatile("s_waitcnt lgkmcnt(" #n ")" ::: "memory")
; #define BAR __builtin_amdgcn_s_barrier()
; #define SCHED __builtin_amdgcn_sched_barrier(0)
; #define STAGE_A(b, h, kt)                                        \
;   do {                                                           \
;     const char* _g = Ab + (h) * halfK + (long)(kt) * 128;        \
;     GLDS2(_g, (unsigned)(((b) * 2 + (h)) * 16384));              \
;   } while (0)
; #define STAGE_B(b, h, kt)                                        \
;   do {                                                           \
;     const char* _g = Bb + (h) * halfK + (long)(kt) * 128;        \
;     GLDS2(_g, (unsigned)(65536 + ((b) * 2 + (h)) * 16384));      \
;   } while (0)
; #define LDA(dst, b, h)                                                                                   \
;   _Pragma("unroll") for (int m = 0; m < 4; ++m) _Pragma("unroll") for (int k = 0; k < 2; ++k) dst[m][k] = \
;       *reinterpret_cast<const bf16x8*>(aRd + ((b) * 2 + (h)) * 16384 + m * 2048 + k * 1024)
; #define LDB(dst, b, h)                                                                                   \
;   _Pragma("unroll") for (int n = 0; n < 2; ++n) _Pragma("unroll") for (int k = 0; k < 2; ++k) dst[n][k] = \
;       *reinterpret_cast<const bf16x8*>(bRd + ((b) * 2 + (h)) * 16384 + n * 2048 + k * 1024)
; template <int EPI> ...
;     ...
;     MMA(1, 0, At, B0);
;     BAR;
;     SCHED;
;     STAGE_B(1, 1, t + 3);
;     WAIT_V(6);
;     BAR;
;     MMA(1, 1, At, B1);
;     BAR;
;   }
;   {
;     LDB(B0, 0, 0);
;     LDA(At, 0, 0);
;     STAGE_A(1, 1, nt - 1);
;     BAR;
;     WAIT_L(0);
;     MMA(0, 0, At, B0);
;     BAR;
;     LDB(B1, 0, 1);
;     BAR;
;     WAIT_L(0);
;     MMA(0, 1, At, B1);
;     BAR;
	s_waitcnt lgkmcnt(0)
	v_mfma_f32_16x16x32_bf16 v[62:65], v[138:141], v[154:157], v[62:65]
	v_mfma_f32_16x16x32_bf16 v[62:65], v[142:145], v[158:161], v[62:65]
	v_mfma_f32_16x16x32_bf16 v[58:61], v[150:153], v[158:161], v[58:61]
	v_mfma_f32_16x16x32_bf16 v[58:61], v[146:149], v[154:157], v[58:61]
	v_mfma_f32_16x16x32_bf16 v[50:53], v[146:149], v[162:165], v[50:53]
	v_mfma_f32_16x16x32_bf16 v[50:53], v[150:153], v[170:173], v[50:53]
	v_mfma_f32_16x16x32_bf16 v[54:57], v[142:145], v[170:173], v[54:57]
	v_mfma_f32_16x16x32_bf16 v[54:57], v[138:141], v[162:165], v[54:57]
	v_mfma_f32_16x16x32_bf16 v[46:49], v[138:141], v[174:177], v[46:49]
	v_mfma_f32_16x16x32_bf16 v[46:49], v[142:145], v[178:181], v[46:49]
	v_mfma_f32_16x16x32_bf16 v[42:45], v[150:153], v[178:181], v[42:45]
	v_mfma_f32_16x16x32_bf16 v[42:45], v[146:149], v[174:177], v[42:45]
	v_mfma_f32_16x16x32_bf16 v[34:37], v[146:149], v[182:185], v[34:37]
	v_mfma_f32_16x16x32_bf16 v[34:37], v[150:153], v[186:189], v[34:37]
	v_mfma_f32_16x16x32_bf16 v[38:41], v[142:145], v[186:189], v[38:41]
	v_mfma_f32_16x16x32_bf16 v[38:41], v[138:141], v[182:185], v[38:41]
	s_barrier
	s_add_u32 s74, s83, 0x180
	s_addc_u32 s75, s84, 0
	s_mov_b32 m0, s8
	s_nop 0
	global_load_lds_dwordx4 v132, s[74:75]
	s_nop 0
	s_mov_b32 m0, s9
	s_nop 0
	global_load_lds_dwordx4 v131, s[74:75]
	s_waitcnt vmcnt(6)
	s_barrier
	v_mfma_f32_16x16x32_bf16 v[30:33], v[220:223], v[154:157], v[30:33]
	v_mfma_f32_16x16x32_bf16 v[30:33], v[224:227], v[158:161], v[30:33]
	v_mfma_f32_16x16x32_bf16 v[26:29], v[232:235], v[158:161], v[26:29]
	v_mfma_f32_16x16x32_bf16 v[26:29], v[228:231], v[154:157], v[26:29]
	v_mfma_f32_16x16x32_bf16 v[18:21], v[228:231], v[162:165], v[18:21]
	v_mfma_f32_16x16x32_bf16 v[18:21], v[232:235], v[170:173], v[18:21]
	v_mfma_f32_16x16x32_bf16 v[22:25], v[224:227], v[170:173], v[22:25]
	v_mfma_f32_16x16x32_bf16 v[22:25], v[220:223], v[162:165], v[22:25]
	v_mfma_f32_16x16x32_bf16 v[14:17], v[220:223], v[174:177], v[14:17]
	v_mfma_f32_16x16x32_bf16 v[14:17], v[224:227], v[178:181], v[14:17]
	v_mfma_f32_16x16x32_bf16 v[10:13], v[232:235], v[178:181], v[10:13]
	v_mfma_f32_16x16x32_bf16 v[10:13], v[228:231], v[174:177], v[10:13]
	v_mfma_f32_16x16x32_bf16 v[2:5], v[228:231], v[182:185], v[2:5]
	v_mfma_f32_16x16x32_bf16 v[2:5], v[232:235], v[186:189], v[2:5]
	v_mfma_f32_16x16x32_bf16 v[6:9], v[224:227], v[186:189], v[6:9]
	v_mfma_f32_16x16x32_bf16 v[6:9], v[220:223], v[182:185], v[6:9]
	s_add_i32 s37, s37, 2
	s_add_u32 s12, s12, 0x100
	s_addc_u32 s13, s13, 0
	s_cmp_lt_u32 s37, 28
	s_barrier
	s_cbranch_scc1 .LBB0_415
	ds_read_b128 v[138:141], v136
	ds_read_b128 v[142:145], v136 offset:1024
	ds_read_b128 v[146:149], v136 offset:2048
	ds_read_b128 v[150:153], v136 offset:3072
	ds_read_b128 v[154:157], v135
	ds_read_b128 v[158:161], v135 offset:1024
	ds_read_b128 v[162:165], v135 offset:2048
	ds_read_b128 v[170:173], v135 offset:3072
	ds_read_b128 v[174:177], v135 offset:4096
	ds_read_b128 v[178:181], v135 offset:5120
	ds_read_b128 v[182:185], v135 offset:6144
	ds_read_b128 v[186:189], v135 offset:7168
	s_add_u32 s6, s18, 0x80f80
	s_addc_u32 s7, s19, 0
	s_mov_b32 m0, s62
	s_nop 0
	global_load_lds_dwordx4 v132, s[6:7]
	s_nop 0
	s_mov_b32 m0, s59
	s_nop 0
	global_load_lds_dwordx4 v131, s[6:7]
	s_barrier
	s_waitcnt lgkmcnt(0)
	v_mfma_f32_16x16x32_bf16 v[126:129], v[138:141], v[154:157], v[126:129]
	v_mfma_f32_16x16x32_bf16 v[126:129], v[142:145], v[158:161], v[126:129]
	v_mfma_f32_16x16x32_bf16 v[122:125], v[150:153], v[158:161], v[122:125]
	v_mfma_f32_16x16x32_bf16 v[122:125], v[146:149], v[154:157], v[122:125]
	v_mfma_f32_16x16x32_bf16 v[114:117], v[146:149], v[162:165], v[114:117]
	v_mfma_f32_16x16x32_bf16 v[114:117], v[150:153], v[170:173], v[114:117]
	v_mfma_f32_16x16x32_bf16 v[118:121], v[142:145], v[170:173], v[118:121]
	v_mfma_f32_16x16x32_bf16 v[118:121], v[138:141], v[162:165], v[118:121]
	v_mfma_f32_16x16x32_bf16 v[110:113], v[138:141], v[174:177], v[110:113]
	v_mfma_f32_16x16x32_bf16 v[110:113], v[142:145], v[178:181], v[110:113]
	v_mfma_f32_16x16x32_bf16 v[106:109], v[150:153], v[178:181], v[106:109]
	v_mfma_f32_16x16x32_bf16 v[106:109], v[146:149], v[174:177], v[106:109]
	v_mfma_f32_16x16x32_bf16 v[98:101], v[146:149], v[182:185], v[98:101]
	v_mfma_f32_16x16x32_bf16 v[98:101], v[150:153], v[186:189], v[98:101]
	v_mfma_f32_16x16x32_bf16 v[102:105], v[142:145], v[186:189], v[102:105]
	v_mfma_f32_16x16x32_bf16 v[102:105], v[138:141], v[182:185], v[102:105]
	s_barrier
	ds_read_b128 v[220:223], v136 offset:16384
	ds_read_b128 v[224:227], v136 offset:17408
	ds_read_b128 v[228:231], v136 offset:18432
	ds_read_b128 v[232:235], v136 offset:19456
	s_barrier
	s_waitcnt lgkmcnt(0)
	v_mfma_f32_16x16x32_bf16 v[94:97], v[220:223], v[154:157], v[94:97]
	v_mfma_f32_16x16x32_bf16 v[94:97], v[224:227], v[158:161], v[94:97]
	v_mfma_f32_16x16x32_bf16 v[90:93], v[232:235], v[158:161], v[90:93]
	v_mfma_f32_16x16x32_bf16 v[90:93], v[228:231], v[154:157], v[90:93]
	v_mfma_f32_16x16x32_bf16 v[82:85], v[228:231], v[162:165], v[82:85]
	v_mfma_f32_16x16x32_bf16 v[82:85], v[232:235], v[170:173], v[82:85]
	v_mfma_f32_16x16x32_bf16 v[86:89], v[224:227], v[170:173], v[86:89]
	v_mfma_f32_16x16x32_bf16 v[86:89], v[220:223], v[162:165], v[86:89]
	v_mfma_f32_16x16x32_bf16 v[78:81], v[220:223], v[174:177], v[78:81]
	v_mfma_f32_16x16x32_bf16 v[78:81], v[224:227], v[178:181], v[78:81]
	v_mfma_f32_16x16x32_bf16 v[74:77], v[232:235], v[178:181], v[74:77]
	v_mfma_f32_16x16x32_bf16 v[74:77], v[228:231], v[174:177], v[74:77]
	v_mfma_f32_16x16x32_bf16 v[66:69], v[228:231], v[182:185], v[66:69]
	v_mfma_f32_16x16x32_bf16 v[66:69], v[232:235], v[186:189], v[66:69]
	v_mfma_f32_16x16x32_bf16 v[70:73], v[224:227], v[186:189], v[70:73]
	v_mfma_f32_16x16x32_bf16 v[70:73], v[220:223], v[182:185], v[70:73]
	s_barrier
; #define WAIT_V(n) asm volatile("s_waitcnt vmcnt(" #n ")" ::: "memory")
; #define WAIT_L(n) asm volatile("s_waitcnt lgkmcnt(" #n ")" ::: "memory")
; #define BAR __builtin_amdgcn_s_barrier()
; #define LDA(dst, b, h)                                                                                   \
;   _Pragma("unroll") for (int m = 0; m < 4; ++m) _Pragma("unroll") for (int k = 0; k < 2; ++k) dst[m][k] = \
;       *reinterpret_cast<const bf16x8*>(aRd + ((b) * 2 + (h)) * 16384 + m * 2048 + k * 1024)
; #define LDB(dst, b, h)                                                                                   \
;   _Pragma("unroll") for (int n = 0; n < 2; ++n) _Pragma("unroll") for (int k = 0; k < 2; ++k) dst[n][k] = \
;       *reinterpret_cast<const bf16x8*>(bRd + ((b) * 2 + (h)) * 16384 + n * 2048 + k * 1024)
; template <int EPI> ...
;     ...
;     LDA(At, 0, 1);
;     WAIT_V(4);
;     BAR;
;     WAIT_L(0);
;     MMA(1, 0, At, B0);
;     MMA(1, 1, At, B1);
;     BAR;
;   }
;   {
;     LDB(B0, 1, 0);
;     LDA(At, 1, 0);
;     WAIT_V(2);
;     BAR;
;     WAIT_L(0);
;     MMA(0, 0, At, B0);
	ds_read_b128 v[154:157], v135 offset:16384
	ds_read_b128 v[158:161], v135 offset:17408
	ds_read_b128 v[162:165], v135 offset:18432
	ds_read_b128 v[170:173], v135 offset:19456
	ds_read_b128 v[174:177], v135 offset:20480
	ds_read_b128 v[178:181], v135 offset:21504
	ds_read_b128 v[182:185], v135 offset:22528
	ds_read_b128 v[186:189], v135 offset:23552
	s_waitcnt vmcnt(4)
	s_barrier
	s_waitcnt lgkmcnt(0)
	v_mfma_f32_16x16x32_bf16 v[62:65], v[138:141], v[154:157], v[62:65]
	v_mfma_f32_16x16x32_bf16 v[62:65], v[142:145], v[158:161], v[62:65]
	v_mfma_f32_16x16x32_bf16 v[58:61], v[150:153], v[158:161], v[58:61]
	v_mfma_f32_16x16x32_bf16 v[58:61], v[146:149], v[154:157], v[58:61]
	v_mfma_f32_16x16x32_bf16 v[50:53], v[146:149], v[162:165], v[50:53]
	v_mfma_f32_16x16x32_bf16 v[50:53], v[150:153], v[170:173], v[50:53]
	v_mfma_f32_16x16x32_bf16 v[54:57], v[142:145], v[170:173], v[54:57]
	v_mfma_f32_16x16x32_bf16 v[54:57], v[138:141], v[162:165], v[54:57]
	v_mfma_f32_16x16x32_bf16 v[46:49], v[138:141], v[174:177], v[46:49]
	v_mfma_f32_16x16x32_bf16 v[46:49], v[142:145], v[178:181], v[46:49]
	v_mfma_f32_16x16x32_bf16 v[42:45], v[150:153], v[178:181], v[42:45]
	v_mfma_f32_16x16x32_bf16 v[42:45], v[146:149], v[174:177], v[42:45]
	v_mfma_f32_16x16x32_bf16 v[34:37], v[146:149], v[182:185], v[34:37]
	v_mfma_f32_16x16x32_bf16 v[34:37], v[150:153], v[186:189], v[34:37]
	v_mfma_f32_16x16x32_bf16 v[38:41], v[142:145], v[186:189], v[38:41]
	v_mfma_f32_16x16x32_bf16 v[38:41], v[138:141], v[182:185], v[38:41]
	v_mfma_f32_16x16x32_bf16 v[30:33], v[220:223], v[154:157], v[30:33]
	v_mfma_f32_16x16x32_bf16 v[30:33], v[224:227], v[158:161], v[30:33]
	v_mfma_f32_16x16x32_bf16 v[26:29], v[232:235], v[158:161], v[26:29]
	v_mfma_f32_16x16x32_bf16 v[26:29], v[228:231], v[154:157], v[26:29]
	v_mfma_f32_16x16x32_bf16 v[18:21], v[228:231], v[162:165], v[18:21]
	v_mfma_f32_16x16x32_bf16 v[18:21], v[232:235], v[170:173], v[18:21]
	v_mfma_f32_16x16x32_bf16 v[22:25], v[224:227], v[170:173], v[22:25]
	v_mfma_f32_16x16x32_bf16 v[22:25], v[220:223], v[162:165], v[22:25]
	v_mfma_f32_16x16x32_bf16 v[14:17], v[220:223], v[174:177], v[14:17]
	v_mfma_f32_16x16x32_bf16 v[14:17], v[224:227], v[178:181], v[14:17]
	v_mfma_f32_16x16x32_bf16 v[10:13], v[232:235], v[178:181], v[10:13]
	v_mfma_f32_16x16x32_bf16 v[10:13], v[228:231], v[174:177], v[10:13]
	v_mfma_f32_16x16x32_bf16 v[2:5], v[228:231], v[182:185], v[2:5]
	v_mfma_f32_16x16x32_bf16 v[2:5], v[232:235], v[186:189], v[2:5]
	v_mfma_f32_16x16x32_bf16 v[6:9], v[224:227], v[186:189], v[6:9]
	v_mfma_f32_16x16x32_bf16 v[6:9], v[220:223], v[182:185], v[6:9]
	s_barrier
	ds_read_b128 v[138:141], v136 offset:32768
	ds_read_b128 v[142:145], v136 offset:33792
	ds_read_b128 v[146:149], v136 offset:34816
	ds_read_b128 v[150:153], v136 offset:35840
	ds_read_b128 v[154:157], v135 offset:32768
	ds_read_b128 v[158:161], v135 offset:33792
	ds_read_b128 v[162:165], v135 offset:34816
	ds_read_b128 v[170:173], v135 offset:35840
	ds_read_b128 v[174:177], v135 offset:36864
	ds_read_b128 v[178:181], v135 offset:37888
	ds_read_b128 v[182:185], v135 offset:38912
	ds_read_b128 v[186:189], v135 offset:39936
	s_waitcnt vmcnt(2)
	s_barrier
	s_waitcnt lgkmcnt(0)
	v_mfma_f32_16x16x32_bf16 v[126:129], v[138:141], v[154:157], v[126:129]
	v_mfma_f32_16x16x32_bf16 v[126:129], v[142:145], v[158:161], v[126:129]
	v_mfma_f32_16x16x32_bf16 v[122:125], v[150:153], v[158:161], v[122:125]
	v_mfma_f32_16x16x32_bf16 v[122:125], v[146:149], v[154:157], v[122:125]
	v_mfma_f32_16x16x32_bf16 v[114:117], v[146:149], v[162:165], v[114:117]
	v_mfma_f32_16x16x32_bf16 v[114:117], v[150:153], v[170:173], v[114:117]
	v_mfma_f32_16x16x32_bf16 v[118:121], v[142:145], v[170:173], v[118:121]
	v_mfma_f32_16x16x32_bf16 v[118:121], v[138:141], v[162:165], v[118:121]
	v_mfma_f32_16x16x32_bf16 v[110:113], v[138:141], v[174:177], v[110:113]
	v_mfma_f32_16x16x32_bf16 v[110:113], v[142:145], v[178:181], v[110:113]
	v_mfma_f32_16x16x32_bf16 v[106:109], v[150:153], v[178:181], v[106:109]
	v_mfma_f32_16x16x32_bf16 v[106:109], v[146:149], v[174:177], v[106:109]
	v_mfma_f32_16x16x32_bf16 v[98:101], v[146:149], v[182:185], v[98:101]
	v_mfma_f32_16x16x32_bf16 v[98:101], v[150:153], v[186:189], v[98:101]
	v_mfma_f32_16x16x32_bf16 v[102:105], v[142:145], v[186:189], v[102:105]
	v_mfma_f32_16x16x32_bf16 v[102:105], v[138:141], v[182:185], v[102:105]
	s_barrier
; #define WAIT_V(n) asm volatile("s_waitcnt vmcnt(" #n ")" ::: "memory")
; #define WAIT_L(n) asm volatile("s_waitcnt lgkmcnt(" #n ")" ::: "memory")
; #define BAR __builtin_amdgcn_s_barrier()
; #define LDA(dst, b, h)                                                                                   \
;   _Pragma("unroll") for (int m = 0; m < 4; ++m) _Pragma("unroll") for (int k = 0; k < 2; ++k) dst[m][k] = \
;       *reinterpret_cast<const bf16x8*>(aRd + ((b) * 2 + (h)) * 16384 + m * 2048 + k * 1024)
; #define LDB(dst, b, h)                                                                                   \
;   _Pragma("unroll") for (int n = 0; n < 2; ++n) _Pragma("unroll") for (int k = 0; k < 2; ++k) dst[n][k] = \
;       *reinterpret_cast<const bf16x8*>(bRd + ((b) * 2 + (h)) * 16384 + n * 2048 + k * 1024)
; template <int EPI> ...
;     ...
;     LDB(B1, 1, 1);
;     WAIT_V(0);
;     BAR;
;     WAIT_L(0);
;     MMA(0, 1, At, B1);
;     BAR;
;     LDA(At, 1, 1);
;     BAR;
;     WAIT_L(0);
;     MMA(1, 0, At, B0);
;     MMA(1, 1, At, B1);
;     BAR;
;   }
;   if (wr == 0) BAR;
	ds_read_b128 v[220:223], v136 offset:49152
	ds_read_b128 v[224:227], v136 offset:50176
	ds_read_b128 v[228:231], v136 offset:51200
	ds_read_b128 v[232:235], v136 offset:52224
	s_waitcnt vmcnt(0)
	s_barrier
	s_waitcnt lgkmcnt(0)
	v_mfma_f32_16x16x32_bf16 v[94:97], v[220:223], v[154:157], v[94:97]
	v_mfma_f32_16x16x32_bf16 v[94:97], v[224:227], v[158:161], v[94:97]
	v_mfma_f32_16x16x32_bf16 v[90:93], v[232:235], v[158:161], v[90:93]
	v_mfma_f32_16x16x32_bf16 v[90:93], v[228:231], v[154:157], v[90:93]
	v_mfma_f32_16x16x32_bf16 v[82:85], v[228:231], v[162:165], v[82:85]
	v_mfma_f32_16x16x32_bf16 v[82:85], v[232:235], v[170:173], v[82:85]
	v_mfma_f32_16x16x32_bf16 v[86:89], v[224:227], v[170:173], v[86:89]
	v_mfma_f32_16x16x32_bf16 v[86:89], v[220:223], v[162:165], v[86:89]
	v_mfma_f32_16x16x32_bf16 v[78:81], v[220:223], v[174:177], v[78:81]
	v_mfma_f32_16x16x32_bf16 v[78:81], v[224:227], v[178:181], v[78:81]
	v_mfma_f32_16x16x32_bf16 v[74:77], v[232:235], v[178:181], v[74:77]
	v_mfma_f32_16x16x32_bf16 v[74:77], v[228:231], v[174:177], v[74:77]
	v_mfma_f32_16x16x32_bf16 v[66:69], v[228:231], v[182:185], v[66:69]
	v_mfma_f32_16x16x32_bf16 v[66:69], v[232:235], v[186:189], v[66:69]
	v_mfma_f32_16x16x32_bf16 v[70:73], v[224:227], v[186:189], v[70:73]
	v_mfma_f32_16x16x32_bf16 v[70:73], v[220:223], v[182:185], v[70:73]
	s_barrier
	ds_read_b128 v[154:157], v135 offset:49152
	ds_read_b128 v[158:161], v135 offset:50176
	ds_read_b128 v[162:165], v135 offset:51200
	ds_read_b128 v[170:173], v135 offset:52224
	ds_read_b128 v[174:177], v135 offset:53248
	ds_read_b128 v[178:181], v135 offset:54272
	ds_read_b128 v[182:185], v135 offset:55296
	ds_read_b128 v[186:189], v135 offset:56320
	s_barrier
	s_waitcnt lgkmcnt(0)
	v_mfma_f32_16x16x32_bf16 v[62:65], v[138:141], v[154:157], v[62:65]
	v_mfma_f32_16x16x32_bf16 v[62:65], v[142:145], v[158:161], v[62:65]
	v_mfma_f32_16x16x32_bf16 v[58:61], v[150:153], v[158:161], v[58:61]
	v_mfma_f32_16x16x32_bf16 v[58:61], v[146:149], v[154:157], v[58:61]
	v_mfma_f32_16x16x32_bf16 v[50:53], v[146:149], v[162:165], v[50:53]
	v_mfma_f32_16x16x32_bf16 v[50:53], v[150:153], v[170:173], v[50:53]
	v_mfma_f32_16x16x32_bf16 v[54:57], v[142:145], v[170:173], v[54:57]
	v_mfma_f32_16x16x32_bf16 v[54:57], v[138:141], v[162:165], v[54:57]
	v_mfma_f32_16x16x32_bf16 v[46:49], v[138:141], v[174:177], v[46:49]
	v_mfma_f32_16x16x32_bf16 v[46:49], v[142:145], v[178:181], v[46:49]
	v_mfma_f32_16x16x32_bf16 v[42:45], v[150:153], v[178:181], v[42:45]
	v_mfma_f32_16x16x32_bf16 v[42:45], v[146:149], v[174:177], v[42:45]
	v_mfma_f32_16x16x32_bf16 v[34:37], v[146:149], v[182:185], v[34:37]
	v_mfma_f32_16x16x32_bf16 v[34:37], v[150:153], v[186:189], v[34:37]
	v_mfma_f32_16x16x32_bf16 v[38:41], v[142:145], v[186:189], v[38:41]
	v_mfma_f32_16x16x32_bf16 v[38:41], v[138:141], v[182:185], v[38:41]
	v_mfma_f32_16x16x32_bf16 v[30:33], v[220:223], v[154:157], v[30:33]
	v_mfma_f32_16x16x32_bf16 v[30:33], v[224:227], v[158:161], v[30:33]
	v_mfma_f32_16x16x32_bf16 v[26:29], v[232:235], v[158:161], v[26:29]
	v_mfma_f32_16x16x32_bf16 v[26:29], v[228:231], v[154:157], v[26:29]
	v_mfma_f32_16x16x32_bf16 v[18:21], v[228:231], v[162:165], v[18:21]
	v_mfma_f32_16x16x32_bf16 v[18:21], v[232:235], v[170:173], v[18:21]
	v_mfma_f32_16x16x32_bf16 v[22:25], v[224:227], v[170:173], v[22:25]
	v_mfma_f32_16x16x32_bf16 v[22:25], v[220:223], v[162:165], v[22:25]
	v_mfma_f32_16x16x32_bf16 v[14:17], v[220:223], v[174:177], v[14:17]
	v_mfma_f32_16x16x32_bf16 v[14:17], v[224:227], v[178:181], v[14:17]
	v_mfma_f32_16x16x32_bf16 v[10:13], v[232:235], v[178:181], v[10:13]
	v_mfma_f32_16x16x32_bf16 v[10:13], v[228:231], v[174:177], v[10:13]
	v_mfma_f32_16x16x32_bf16 v[2:5], v[228:231], v[182:185], v[2:5]
	v_mfma_f32_16x16x32_bf16 v[2:5], v[232:235], v[186:189], v[2:5]
	v_mfma_f32_16x16x32_bf16 v[6:9], v[224:227], v[186:189], v[6:9]
	v_mfma_f32_16x16x32_bf16 v[6:9], v[220:223], v[182:185], v[6:9]
	s_movk_i32 s6, 0x100
	v_cmp_gt_u32_e32 vcc, s6, v133
	s_barrier
	s_and_saveexec_b64 s[12:13], vcc
	s_cbranch_execz .LBB0_418
	s_barrier
